# UP GEMM passes of the 3-m-tile workgroups are claimed from a shared counter by idle same-XCD workgroups (work sharing before the grid barrier)
# speedup vs baseline: 1.0621x; 1.0621x over previous
; DI int otid() { int t = threadIdx.x; asm volatile("" : "+v"(t)); return t; }
; template <int MODE, int MT> DI void norm_rows(const float* src, const float* src2, float* x, int d2, bf16_t* xb, const float* __restrict__ g) {
;     const int tid_ = otid(), wave = tid_ >> 6, lane = tid_ & 63;
;     for (int rb = 0; rb < MT; ++rb) {
;         f32x4 v[4][4]; float ss[4];
; #pragma unroll
;         for (int q = 0; q < 4; ++q) {
;             const int row = wave * (MT * 4) + rb * 4 + q, grow = row + (row >= 64 ? d2 : 0);
;             const float* s = x + (size_t)grow * DM;
;             if (MODE == 0) { s = src + (size_t)row * DM; if (MT == 3 && row >= 64) s = src2 + (size_t)(row - 64) * DM; }
;             ss[q] = 0.f;
; #pragma unroll
;             for (int i = 0; i < 4; ++i) { v[q][i] = *(const f32x4*)(s + i * 256 + lane * 4); ss[q] += v[q][i][0] * v[q][i][0] + v[q][i][1] * v[q][i][1] + v[q][i][2] * v[q][i][2] + v[q][i][3] * v[q][i][3]; }
;         }
.LBB0_457:
	v_mov_b32_e32 v2, v176
	s_waitcnt lgkmcnt(0)
	s_barrier
	v_mov_b32_e32 v3, v1
	v_ashrrev_i32_e32 v94, 6, v2
	v_lshlrev_b32_e32 v2, 2, v2
	v_and_b32_e32 v4, 0xfc, v2
	v_lshlrev_b32_e32 v2, 2, v4
	v_lshl_add_u64 v[68:69], s[0:1], 0, v[2:3]
	v_lshlrev_b32_e32 v2, 1, v4
	v_cmp_lt_i32_e32 vcc, 5, v94
	v_mov_b32_e32 v95, s24
	v_mul_lo_u32 v0, v94, 12
	v_lshl_add_u64 v[66:67], s[34:35], 0, v[2:3]
	v_cndmask_b32_e32 v2, 0, v95, vcc
	v_add_u32_e32 v92, v2, v0
	v_ashrrev_i32_e32 v93, 31, v92
	v_lshlrev_b64 v[2:3], 12, v[92:93]
	v_lshl_add_u64 v[2:3], v[68:69], 0, v[2:3]
	global_load_dwordx4 v[18:21], v[2:3], off
	global_load_dwordx4 v[10:13], v[2:3], off offset:1024
	global_load_dwordx4 v[38:41], v[2:3], off offset:2048
	global_load_dwordx4 v[30:33], v[2:3], off offset:3072
	v_add_u32_e32 v74, 1, v92
	v_ashrrev_i32_e32 v75, 31, v74
	s_mov_b32 s0, 0x358637bd
	s_mov_b32 s4, 0x3a800000
	s_mov_b32 s3, 0x800000
	v_lshlrev_b64 v[92:93], 11, v[92:93]
	v_lshl_add_u64 v[92:93], v[66:67], 0, v[92:93]
	s_mov_b32 s2, 0
	s_mov_b32 s31, 0
	s_waitcnt vmcnt(3)
	v_mov_b32_e32 v6, v19
	s_waitcnt vmcnt(2)
	v_mov_b32_e32 v7, v11
	v_mov_b32_e32 v4, v18
	v_mov_b32_e32 v5, v10
	v_pk_mul_f32 v[6:7], v[6:7], v[6:7]
	s_waitcnt vmcnt(1)
	v_mov_b32_e32 v2, v38
	v_pk_fma_f32 v[4:5], v[4:5], v[4:5], v[6:7]
	v_mov_b32_e32 v6, v20
	v_mov_b32_e32 v7, v12
	v_pk_fma_f32 v[4:5], v[6:7], v[6:7], v[4:5]
	v_mov_b32_e32 v6, v21
	v_mov_b32_e32 v7, v13
	v_pk_fma_f32 v[70:71], v[6:7], v[6:7], v[4:5]
	v_mov_b32_e32 v4, v39
	s_waitcnt vmcnt(0)
	v_mov_b32_e32 v5, v31
	v_mov_b32_e32 v3, v30
	v_pk_mul_f32 v[4:5], v[4:5], v[4:5]
	s_nop 0
	v_pk_fma_f32 v[2:3], v[2:3], v[2:3], v[4:5]
	v_mov_b32_e32 v4, v40
	v_mov_b32_e32 v5, v32
	v_pk_fma_f32 v[2:3], v[4:5], v[4:5], v[2:3]
	v_mov_b32_e32 v4, v41
	v_mov_b32_e32 v5, v33
	v_pk_fma_f32 v[82:83], v[4:5], v[4:5], v[2:3]
	v_lshlrev_b64 v[2:3], 12, v[74:75]
	v_lshl_add_u64 v[2:3], v[68:69], 0, v[2:3]
	global_load_dwordx4 v[50:53], v[2:3], off
	global_load_dwordx4 v[46:49], v[2:3], off offset:1024
	global_load_dwordx4 v[62:65], v[2:3], off offset:2048
	global_load_dwordx4 v[58:61], v[2:3], off offset:3072
	s_waitcnt vmcnt(3)
	v_mov_b32_e32 v6, v51
	s_waitcnt vmcnt(2)
	v_mov_b32_e32 v7, v47
	v_mov_b32_e32 v4, v50
	v_mov_b32_e32 v5, v46
	v_pk_mul_f32 v[6:7], v[6:7], v[6:7]
	s_waitcnt vmcnt(1)
	v_mov_b32_e32 v2, v62
	v_pk_fma_f32 v[4:5], v[4:5], v[4:5], v[6:7]
	v_mov_b32_e32 v6, v52
	v_mov_b32_e32 v7, v48
	v_pk_fma_f32 v[4:5], v[6:7], v[6:7], v[4:5]
	v_mov_b32_e32 v6, v53
	v_mov_b32_e32 v7, v49
	v_pk_fma_f32 v[86:87], v[6:7], v[6:7], v[4:5]
	v_mov_b32_e32 v4, v63
	s_waitcnt vmcnt(0)
	v_mov_b32_e32 v5, v59
	v_mov_b32_e32 v3, v58
	v_pk_mul_f32 v[4:5], v[4:5], v[4:5]
	s_nop 0
	v_pk_fma_f32 v[2:3], v[2:3], v[2:3], v[4:5]
	v_mov_b32_e32 v4, v64
	v_mov_b32_e32 v5, v60
	v_pk_fma_f32 v[2:3], v[4:5], v[4:5], v[2:3]
	v_mov_b32_e32 v4, v65
	v_mov_b32_e32 v5, v61
	v_pk_fma_f32 v[90:91], v[4:5], v[4:5], v[2:3]
	v_or_b32_e32 v2, 2, v0
	v_cmp_lt_i32_e32 vcc, 63, v2
	s_nop 1
	v_cndmask_b32_e32 v3, 0, v95, vcc
	v_add_u32_e32 v80, v3, v2
	v_ashrrev_i32_e32 v81, 31, v80
	v_lshlrev_b64 v[2:3], 12, v[80:81]
	v_lshl_add_u64 v[14:15], v[68:69], 0, v[2:3]
	global_load_dwordx4 v[6:9], v[14:15], off
	global_load_dwordx4 v[2:5], v[14:15], off offset:1024
	s_waitcnt vmcnt(1)
	v_mov_b32_e32 v22, v7
	s_waitcnt vmcnt(0)
	v_mov_b32_e32 v23, v3
	v_mov_b32_e32 v16, v6
	v_mov_b32_e32 v17, v2
	v_pk_mul_f32 v[22:23], v[22:23], v[22:23]
	s_nop 0
	v_pk_fma_f32 v[16:17], v[16:17], v[16:17], v[22:23]
	v_mov_b32_e32 v22, v8
	v_mov_b32_e32 v23, v4
	v_pk_fma_f32 v[16:17], v[22:23], v[22:23], v[16:17]
	v_mov_b32_e32 v22, v9
	v_mov_b32_e32 v23, v5
	v_pk_fma_f32 v[76:77], v[22:23], v[22:23], v[16:17]
	global_load_dwordx4 v[22:25], v[14:15], off offset:2048
	s_nop 0
	global_load_dwordx4 v[14:17], v[14:15], off offset:3072
	s_waitcnt vmcnt(1)
	v_mov_b32_e32 v28, v23
	s_waitcnt vmcnt(0)
	v_mov_b32_e32 v29, v15
	v_mov_b32_e32 v26, v22
	v_mov_b32_e32 v27, v14
	v_pk_mul_f32 v[28:29], v[28:29], v[28:29]
	s_nop 0
	v_pk_fma_f32 v[26:27], v[26:27], v[26:27], v[28:29]
	v_mov_b32_e32 v28, v24
	v_mov_b32_e32 v29, v16
	v_pk_fma_f32 v[26:27], v[28:29], v[28:29], v[26:27]
	v_mov_b32_e32 v28, v25
	v_mov_b32_e32 v29, v17
	v_pk_fma_f32 v[78:79], v[28:29], v[28:29], v[26:27]
	v_or_b32_e32 v26, 3, v0
	v_cmp_lt_i32_e32 vcc, 63, v26
	s_nop 1
	v_cndmask_b32_e32 v27, 0, v95, vcc
	v_add_u32_e32 v72, v27, v26
	v_ashrrev_i32_e32 v73, 31, v72
	v_lshlrev_b64 v[26:27], 12, v[72:73]
	v_lshl_add_u64 v[42:43], v[68:69], 0, v[26:27]
	global_load_dwordx4 v[34:37], v[42:43], off
	global_load_dwordx4 v[26:29], v[42:43], off offset:1024
	s_waitcnt vmcnt(1)
	v_mov_b32_e32 v54, v35
	s_waitcnt vmcnt(0)
	v_mov_b32_e32 v55, v27
	v_mov_b32_e32 v44, v34
	v_mov_b32_e32 v45, v26
	v_pk_mul_f32 v[54:55], v[54:55], v[54:55]
	s_nop 0
	v_pk_fma_f32 v[44:45], v[44:45], v[44:45], v[54:55]
	v_mov_b32_e32 v54, v36
	v_mov_b32_e32 v55, v28
	v_pk_fma_f32 v[44:45], v[54:55], v[54:55], v[44:45]
	v_mov_b32_e32 v54, v37
	v_mov_b32_e32 v55, v29
	v_pk_fma_f32 v[84:85], v[54:55], v[54:55], v[44:45]
	global_load_dwordx4 v[54:57], v[42:43], off offset:2048
	s_nop 0
	global_load_dwordx4 v[42:45], v[42:43], off offset:3072
	s_waitcnt vmcnt(1)
	v_mov_b32_e32 v96, v55
	s_waitcnt vmcnt(0)
	v_mov_b32_e32 v97, v43
	v_mov_b32_e32 v88, v54
	v_mov_b32_e32 v89, v42
	v_pk_mul_f32 v[96:97], v[96:97], v[96:97]
	s_nop 0
	v_pk_fma_f32 v[88:89], v[88:89], v[88:89], v[96:97]
	v_mov_b32_e32 v96, v56
	v_mov_b32_e32 v97, v44
	v_pk_fma_f32 v[88:89], v[96:97], v[96:97], v[88:89]
	v_mov_b32_e32 v96, v57
	v_mov_b32_e32 v97, v45
	v_pk_fma_f32 v[88:89], v[96:97], v[96:97], v[88:89]
	v_mov_b32_e32 v96, v86
	v_mov_b32_e32 v97, v70
	v_mov_b32_e32 v70, v87
	v_pk_add_f32 v[70:71], v[96:97], v[70:71]
	v_mov_b32_e32 v86, v90
	v_mov_b32_e32 v87, v82
	v_pk_add_f32 v[70:71], v[70:71], v[86:87]
	v_mov_b32_e32 v82, v91
	v_pk_add_f32 v[70:71], v[70:71], v[82:83]
	ds_bpermute_b32 v83, v224, v71
	ds_bpermute_b32 v82, v224, v70
	s_waitcnt lgkmcnt(0)
; DI unsigned pk2(float lo, float hi) { f32x2 v = {lo, hi}; bf2_t b = __builtin_convertvector(v, bf2_t); return __builtin_bit_cast(unsigned, b); }
; template <int MODE, int MT> DI void norm_rows(const float* src, const float* src2, float* x, int d2, bf16_t* xb, const float* __restrict__ g) {
;     ...
; #pragma unroll
;         for (int o = 32; o >= 1; o >>= 1)
; #pragma unroll
;             for (int q = 0; q < 4; ++q) ss[q] += __shfl_xor(ss[q], o);
; #pragma unroll
;         for (int q = 0; q < 4; ++q) {
;             const int row = wave * (MT * 4) + rb * 4 + q, grow = row + (row >= 64 ? d2 : 0);
;             const float rstd = rsqrtf(ss[q] * (1.f / DM) + 1e-6f);
; #pragma unroll
;             for (int i = 0; i < 4; ++i) {
;                 if (MODE == 0) *(f32x4*)(x + (size_t)grow * DM + i * 256 + lane * 4) = v[q][i];
;                 if (MODE == 2) { f32x4 gg = *(const f32x4*)(g + i * 256 + lane * 4); *(f32x4*)(x + (size_t)grow * DM + i * 256 + lane * 4) = v[q][i] * rstd * gg; }
;                 else { u32x2 o = {pk2(v[q][i][0] * rstd, v[q][i][1] * rstd), pk2(v[q][i][2] * rstd, v[q][i][3] * rstd)}; *(u32x2*)(xb + (size_t)grow * DM + i * 256 + lane * 4) = o; }
;             }
;         }
	v_pk_add_f32 v[70:71], v[70:71], v[82:83]
	ds_bpermute_b32 v83, v228, v71
	ds_bpermute_b32 v82, v228, v70
	s_waitcnt lgkmcnt(0)
	v_pk_add_f32 v[70:71], v[70:71], v[82:83]
	ds_bpermute_b32 v83, v227, v71
	ds_bpermute_b32 v82, v227, v70
	s_waitcnt lgkmcnt(0)
	v_pk_add_f32 v[70:71], v[70:71], v[82:83]
	ds_bpermute_b32 v83, v226, v71
	ds_bpermute_b32 v82, v226, v70
	s_waitcnt lgkmcnt(0)
	v_pk_add_f32 v[70:71], v[70:71], v[82:83]
	ds_bpermute_b32 v83, v225, v71
	ds_bpermute_b32 v82, v225, v70
	s_waitcnt lgkmcnt(0)
	v_pk_add_f32 v[70:71], v[70:71], v[82:83]
	ds_bpermute_b32 v83, v223, v71
	ds_bpermute_b32 v82, v223, v70
	s_waitcnt lgkmcnt(0)
	v_pk_add_f32 v[82:83], v[70:71], v[82:83]
	v_mov_b64_e32 v[70:71], s[0:1]
	v_pk_fma_f32 v[82:83], v[82:83], s[4:5], v[70:71] op_sel_hi:[1,0,0]
	s_nop 0
	v_mul_f32_e32 v86, 0x4b800000, v83
	v_cmp_gt_f32_e64 s[0:1], s3, v83
	v_cmp_gt_f32_e32 vcc, s3, v82
	s_nop 0
	v_cndmask_b32_e64 v83, v83, v86, s[0:1]
	v_rsq_f32_e32 v83, v83
	s_nop 0
	v_mul_f32_e32 v86, 0x45800000, v83
	v_cndmask_b32_e64 v86, v83, v86, s[0:1]
	v_pk_mul_f32 v[10:11], v[10:11], v[86:87] op_sel_hi:[1,0]
	v_pk_mul_f32 v[12:13], v[12:13], v[86:87] op_sel_hi:[1,0]
	v_cvt_pk_f16_f32 v10, v10, v11
	v_cvt_pk_f16_f32 v11, v12, v13
	global_store_dwordx2 v[92:93], v[10:11], off offset:512
	v_pk_mul_f32 v[10:11], v[38:39], v[86:87] op_sel_hi:[1,0]
	v_pk_mul_f32 v[12:13], v[40:41], v[86:87] op_sel_hi:[1,0]
	v_cvt_pk_f16_f32 v10, v10, v11
	v_cvt_pk_f16_f32 v11, v12, v13
	global_store_dwordx2 v[92:93], v[10:11], off offset:1024
	v_pk_mul_f32 v[10:11], v[30:31], v[86:87] op_sel_hi:[1,0]
	v_pk_mul_f32 v[12:13], v[32:33], v[86:87] op_sel_hi:[1,0]
	v_cvt_pk_f16_f32 v10, v10, v11
	v_cvt_pk_f16_f32 v11, v12, v13
	global_store_dwordx2 v[92:93], v[10:11], off offset:1536
	v_mul_f32_e32 v10, 0x4b800000, v82
	v_cndmask_b32_e32 v10, v82, v10, vcc
	v_rsq_f32_e32 v10, v10
	v_pk_mul_f32 v[18:19], v[18:19], v[86:87] op_sel_hi:[1,0]
	v_pk_mul_f32 v[20:21], v[20:21], v[86:87] op_sel_hi:[1,0]
	v_cvt_pk_f16_f32 v18, v18, v19
	v_mul_f32_e32 v11, 0x45800000, v10
	v_cvt_pk_f16_f32 v19, v20, v21
	v_cndmask_b32_e32 v10, v10, v11, vcc
	global_store_dwordx2 v[92:93], v[18:19], off
	v_lshlrev_b64 v[12:13], 11, v[74:75]
	v_pk_mul_f32 v[18:19], v[50:51], v[10:11] op_sel_hi:[1,0]
	v_pk_mul_f32 v[20:21], v[52:53], v[10:11] op_sel_hi:[1,0]
	v_lshl_add_u64 v[12:13], v[66:67], 0, v[12:13]
	v_cvt_pk_f16_f32 v18, v18, v19
	v_cvt_pk_f16_f32 v19, v20, v21
	global_store_dwordx2 v[12:13], v[18:19], off
	v_pk_mul_f32 v[18:19], v[46:47], v[10:11] op_sel_hi:[1,0]
	v_pk_mul_f32 v[20:21], v[48:49], v[10:11] op_sel_hi:[1,0]
	v_cvt_pk_f16_f32 v18, v18, v19
	v_cvt_pk_f16_f32 v19, v20, v21
	global_store_dwordx2 v[12:13], v[18:19], off offset:512
	v_pk_mul_f32 v[18:19], v[62:63], v[10:11] op_sel_hi:[1,0]
	v_pk_mul_f32 v[20:21], v[64:65], v[10:11] op_sel_hi:[1,0]
	v_cvt_pk_f16_f32 v18, v18, v19
	v_cvt_pk_f16_f32 v19, v20, v21
	global_store_dwordx2 v[12:13], v[18:19], off offset:1024
	v_pk_mul_f32 v[18:19], v[58:59], v[10:11] op_sel_hi:[1,0]
	v_pk_mul_f32 v[10:11], v[60:61], v[10:11] op_sel_hi:[1,0]
	v_cvt_pk_f16_f32 v18, v18, v19
	v_cvt_pk_f16_f32 v19, v10, v11
	global_store_dwordx2 v[12:13], v[18:19], off offset:1536
	v_mov_b32_e32 v12, v84
	v_mov_b32_e32 v13, v76
	v_mov_b32_e32 v76, v85
	v_pk_add_f32 v[12:13], v[12:13], v[76:77]
	v_mov_b32_e32 v18, v88
	v_mov_b32_e32 v19, v78
	v_pk_add_f32 v[12:13], v[12:13], v[18:19]
	v_mov_b32_e32 v78, v89
	v_pk_add_f32 v[12:13], v[12:13], v[78:79]
	ds_bpermute_b32 v19, v224, v13
	ds_bpermute_b32 v18, v224, v12
	v_lshlrev_b64 v[10:11], 11, v[80:81]
	v_lshl_add_u64 v[10:11], v[66:67], 0, v[10:11]
	s_waitcnt lgkmcnt(0)
	v_pk_add_f32 v[12:13], v[12:13], v[18:19]
	ds_bpermute_b32 v19, v228, v13
	ds_bpermute_b32 v18, v228, v12
	s_waitcnt lgkmcnt(0)
	v_pk_add_f32 v[12:13], v[12:13], v[18:19]
	ds_bpermute_b32 v19, v227, v13
	ds_bpermute_b32 v18, v227, v12
	s_waitcnt lgkmcnt(0)
	v_pk_add_f32 v[12:13], v[12:13], v[18:19]
	ds_bpermute_b32 v19, v226, v13
	ds_bpermute_b32 v18, v226, v12
	s_waitcnt lgkmcnt(0)
	v_pk_add_f32 v[12:13], v[12:13], v[18:19]
	ds_bpermute_b32 v19, v225, v13
	ds_bpermute_b32 v18, v225, v12
	s_waitcnt lgkmcnt(0)
	v_pk_add_f32 v[12:13], v[12:13], v[18:19]
	ds_bpermute_b32 v19, v223, v13
	ds_bpermute_b32 v18, v223, v12
	s_waitcnt lgkmcnt(0)
; DI unsigned pk2(float lo, float hi) { f32x2 v = {lo, hi}; bf2_t b = __builtin_convertvector(v, bf2_t); return __builtin_bit_cast(unsigned, b); }
; template <int MODE, int MT> DI void norm_rows(const float* src, const float* src2, float* x, int d2, bf16_t* xb, const float* __restrict__ g) {
;     ...
;     for (int rb = 0; rb < MT; ++rb) {
;         f32x4 v[4][4]; float ss[4];
; #pragma unroll
;         for (int q = 0; q < 4; ++q) {
;             const int row = wave * (MT * 4) + rb * 4 + q, grow = row + (row >= 64 ? d2 : 0);
;             const float* s = x + (size_t)grow * DM;
;             if (MODE == 0) { s = src + (size_t)row * DM; if (MT == 3 && row >= 64) s = src2 + (size_t)(row - 64) * DM; }
;             ss[q] = 0.f;
; #pragma unroll
;             for (int i = 0; i < 4; ++i) { v[q][i] = *(const f32x4*)(s + i * 256 + lane * 4); ss[q] += v[q][i][0] * v[q][i][0] + v[q][i][1] * v[q][i][1] + v[q][i][2] * v[q][i][2] + v[q][i][3] * v[q][i][3]; }
;         }
; #pragma unroll
;         for (int o = 32; o >= 1; o >>= 1)
; #pragma unroll
;             for (int q = 0; q < 4; ++q) ss[q] += __shfl_xor(ss[q], o);
; #pragma unroll
;         for (int q = 0; q < 4; ++q) {
;             const int row = wave * (MT * 4) + rb * 4 + q, grow = row + (row >= 64 ? d2 : 0);
;             const float rstd = rsqrtf(ss[q] * (1.f / DM) + 1e-6f);
; #pragma unroll
;             for (int i = 0; i < 4; ++i) {
;                 if (MODE == 0) *(f32x4*)(x + (size_t)grow * DM + i * 256 + lane * 4) = v[q][i];
;                 if (MODE == 2) { f32x4 gg = *(const f32x4*)(g + i * 256 + lane * 4); *(f32x4*)(x + (size_t)grow * DM + i * 256 + lane * 4) = v[q][i] * rstd * gg; }
;                 else { u32x2 o = {pk2(v[q][i][0] * rstd, v[q][i][1] * rstd), pk2(v[q][i][2] * rstd, v[q][i][3] * rstd)}; *(u32x2*)(xb + (size_t)grow * DM + i * 256 + lane * 4) = o; }
;             }
;         }
	v_pk_add_f32 v[12:13], v[12:13], v[18:19]
	s_nop 0
	v_pk_fma_f32 v[12:13], v[12:13], s[4:5], v[70:71] op_sel_hi:[1,0,0]
	s_nop 0
	v_mul_f32_e32 v18, 0x4b800000, v13
	v_cmp_gt_f32_e64 s[0:1], s3, v13
	v_cmp_gt_f32_e32 vcc, s3, v12
	s_nop 0
	v_cndmask_b32_e64 v13, v13, v18, s[0:1]
	v_rsq_f32_e32 v13, v13
	s_nop 0
	v_mul_f32_e32 v18, 0x45800000, v13
	v_cndmask_b32_e64 v18, v13, v18, s[0:1]
	v_pk_mul_f32 v[2:3], v[2:3], v[18:19] op_sel_hi:[1,0]
	v_pk_mul_f32 v[4:5], v[4:5], v[18:19] op_sel_hi:[1,0]
	v_cvt_pk_f16_f32 v2, v2, v3
	v_cvt_pk_f16_f32 v3, v4, v5
	global_store_dwordx2 v[10:11], v[2:3], off offset:512
	v_pk_mul_f32 v[2:3], v[22:23], v[18:19] op_sel_hi:[1,0]
	v_pk_mul_f32 v[4:5], v[24:25], v[18:19] op_sel_hi:[1,0]
	v_cvt_pk_f16_f32 v2, v2, v3
	v_cvt_pk_f16_f32 v3, v4, v5
	global_store_dwordx2 v[10:11], v[2:3], off offset:1024
	v_pk_mul_f32 v[2:3], v[14:15], v[18:19] op_sel_hi:[1,0]
	v_pk_mul_f32 v[4:5], v[16:17], v[18:19] op_sel_hi:[1,0]
	v_cvt_pk_f16_f32 v2, v2, v3
	v_cvt_pk_f16_f32 v3, v4, v5
	global_store_dwordx2 v[10:11], v[2:3], off offset:1536
	v_mul_f32_e32 v2, 0x4b800000, v12
	v_cndmask_b32_e32 v2, v12, v2, vcc
	v_rsq_f32_e32 v2, v2
	v_pk_mul_f32 v[6:7], v[6:7], v[18:19] op_sel_hi:[1,0]
	v_pk_mul_f32 v[8:9], v[8:9], v[18:19] op_sel_hi:[1,0]
	v_cvt_pk_f16_f32 v6, v6, v7
	v_mul_f32_e32 v3, 0x45800000, v2
	v_cvt_pk_f16_f32 v7, v8, v9
	v_cndmask_b32_e32 v2, v2, v3, vcc
	global_store_dwordx2 v[10:11], v[6:7], off
	v_lshlrev_b64 v[4:5], 11, v[72:73]
	v_pk_mul_f32 v[6:7], v[34:35], v[2:3] op_sel_hi:[1,0]
	v_pk_mul_f32 v[8:9], v[36:37], v[2:3] op_sel_hi:[1,0]
	v_lshl_add_u64 v[4:5], v[66:67], 0, v[4:5]
	v_cvt_pk_f16_f32 v6, v6, v7
	v_cvt_pk_f16_f32 v7, v8, v9
	global_store_dwordx2 v[4:5], v[6:7], off
	v_pk_mul_f32 v[6:7], v[26:27], v[2:3] op_sel_hi:[1,0]
	v_pk_mul_f32 v[8:9], v[28:29], v[2:3] op_sel_hi:[1,0]
	v_cvt_pk_f16_f32 v6, v6, v7
	v_cvt_pk_f16_f32 v7, v8, v9
	global_store_dwordx2 v[4:5], v[6:7], off offset:512
	v_pk_mul_f32 v[6:7], v[54:55], v[2:3] op_sel_hi:[1,0]
	v_pk_mul_f32 v[8:9], v[56:57], v[2:3] op_sel_hi:[1,0]
	v_cvt_pk_f16_f32 v6, v6, v7
	v_cvt_pk_f16_f32 v7, v8, v9
	global_store_dwordx2 v[4:5], v[6:7], off offset:1024
	v_pk_mul_f32 v[6:7], v[42:43], v[2:3] op_sel_hi:[1,0]
	v_pk_mul_f32 v[2:3], v[44:45], v[2:3] op_sel_hi:[1,0]
	v_cmp_lt_i32_e32 vcc, 4, v94
	v_cvt_pk_f16_f32 v6, v6, v7
	v_cvt_pk_f16_f32 v7, v2, v3
	v_cndmask_b32_e32 v2, 0, v95, vcc
	v_add_u32_e32 v0, v2, v0
	v_add_u32_e32 v92, 4, v0
	v_ashrrev_i32_e32 v93, 31, v92
	v_lshlrev_b64 v[2:3], 12, v[92:93]
	global_store_dwordx2 v[4:5], v[6:7], off offset:1536
	v_lshl_add_u64 v[2:3], v[68:69], 0, v[2:3]
	global_load_dwordx4 v[18:21], v[2:3], off
	global_load_dwordx4 v[10:13], v[2:3], off offset:1024
	global_load_dwordx4 v[34:37], v[2:3], off offset:2048
	global_load_dwordx4 v[26:29], v[2:3], off offset:3072
	v_add_u32_e32 v74, 5, v0
	v_ashrrev_i32_e32 v75, 31, v74
	v_add_u32_e32 v82, 6, v0
	v_ashrrev_i32_e32 v83, 31, v82
	v_add_u32_e32 v72, 7, v0
	v_ashrrev_i32_e32 v73, 31, v72
	v_lshlrev_b64 v[92:93], 11, v[92:93]
	v_lshl_add_u64 v[92:93], v[66:67], 0, v[92:93]
	s_waitcnt vmcnt(3)
	v_mov_b32_e32 v6, v19
	s_waitcnt vmcnt(2)
	v_mov_b32_e32 v7, v11
	v_mov_b32_e32 v4, v18
	v_mov_b32_e32 v5, v10
	v_pk_mul_f32 v[6:7], v[6:7], v[6:7]
	s_waitcnt vmcnt(1)
	v_mov_b32_e32 v2, v34
	v_pk_fma_f32 v[4:5], v[4:5], v[4:5], v[6:7]
	v_mov_b32_e32 v6, v20
	v_mov_b32_e32 v7, v12
	v_pk_fma_f32 v[4:5], v[6:7], v[6:7], v[4:5]
	v_mov_b32_e32 v6, v21
	v_mov_b32_e32 v7, v13
	v_pk_fma_f32 v[78:79], v[6:7], v[6:7], v[4:5]
	v_mov_b32_e32 v4, v35
	s_waitcnt vmcnt(0)
	v_mov_b32_e32 v5, v27
	v_mov_b32_e32 v3, v26
	v_pk_mul_f32 v[4:5], v[4:5], v[4:5]
	s_nop 0
	v_pk_fma_f32 v[2:3], v[2:3], v[2:3], v[4:5]
	v_mov_b32_e32 v4, v36
	v_mov_b32_e32 v5, v28
	v_pk_fma_f32 v[2:3], v[4:5], v[4:5], v[2:3]
	v_mov_b32_e32 v4, v37
	v_mov_b32_e32 v5, v29
	v_pk_fma_f32 v[84:85], v[4:5], v[4:5], v[2:3]
	v_lshlrev_b64 v[2:3], 12, v[74:75]
	v_lshl_add_u64 v[2:3], v[68:69], 0, v[2:3]
	global_load_dwordx4 v[46:49], v[2:3], off
	global_load_dwordx4 v[42:45], v[2:3], off offset:1024
	global_load_dwordx4 v[54:57], v[2:3], off offset:2048
	global_load_dwordx4 v[50:53], v[2:3], off offset:3072
	s_waitcnt vmcnt(3)
	v_mov_b32_e32 v6, v47
	s_waitcnt vmcnt(2)
	v_mov_b32_e32 v7, v43
	v_mov_b32_e32 v4, v46
	v_mov_b32_e32 v5, v42
	v_pk_mul_f32 v[6:7], v[6:7], v[6:7]
	s_waitcnt vmcnt(1)
	v_mov_b32_e32 v2, v54
	v_pk_fma_f32 v[4:5], v[4:5], v[4:5], v[6:7]
	v_mov_b32_e32 v6, v48
	v_mov_b32_e32 v7, v44
	v_pk_fma_f32 v[4:5], v[6:7], v[6:7], v[4:5]
	v_mov_b32_e32 v6, v49
	v_mov_b32_e32 v7, v45
	v_pk_fma_f32 v[88:89], v[6:7], v[6:7], v[4:5]
	v_mov_b32_e32 v4, v55
	s_waitcnt vmcnt(0)
	v_mov_b32_e32 v5, v51
	v_mov_b32_e32 v3, v50
	v_pk_mul_f32 v[4:5], v[4:5], v[4:5]
	s_nop 0
	v_pk_fma_f32 v[2:3], v[2:3], v[2:3], v[4:5]
	v_mov_b32_e32 v4, v56
	v_mov_b32_e32 v5, v52
	v_pk_fma_f32 v[2:3], v[4:5], v[4:5], v[2:3]
	v_mov_b32_e32 v4, v57
	v_mov_b32_e32 v5, v53
	v_pk_fma_f32 v[90:91], v[4:5], v[4:5], v[2:3]
	v_lshlrev_b64 v[2:3], 12, v[82:83]
	v_lshl_add_u64 v[14:15], v[68:69], 0, v[2:3]
	global_load_dwordx4 v[6:9], v[14:15], off
	global_load_dwordx4 v[2:5], v[14:15], off offset:1024
	s_waitcnt vmcnt(1)
	v_mov_b32_e32 v22, v7
	s_waitcnt vmcnt(0)
	v_mov_b32_e32 v23, v3
	v_mov_b32_e32 v16, v6
	v_mov_b32_e32 v17, v2
	v_pk_mul_f32 v[22:23], v[22:23], v[22:23]
	s_nop 0
	v_pk_fma_f32 v[16:17], v[16:17], v[16:17], v[22:23]
	v_mov_b32_e32 v22, v8
	v_mov_b32_e32 v23, v4
	v_pk_fma_f32 v[16:17], v[22:23], v[22:23], v[16:17]
	v_mov_b32_e32 v22, v9
	v_mov_b32_e32 v23, v5
	v_pk_fma_f32 v[76:77], v[22:23], v[22:23], v[16:17]
	global_load_dwordx4 v[22:25], v[14:15], off offset:2048
	s_nop 0
	global_load_dwordx4 v[14:17], v[14:15], off offset:3072
	s_waitcnt vmcnt(1)
; DI unsigned pk2(float lo, float hi) { f32x2 v = {lo, hi}; bf2_t b = __builtin_convertvector(v, bf2_t); return __builtin_bit_cast(unsigned, b); }
; template <int MODE, int MT> DI void norm_rows(const float* src, const float* src2, float* x, int d2, bf16_t* xb, const float* __restrict__ g) {
;     ...
;     for (int rb = 0; rb < MT; ++rb) {
;         f32x4 v[4][4]; float ss[4];
; #pragma unroll
;         for (int q = 0; q < 4; ++q) {
;             const int row = wave * (MT * 4) + rb * 4 + q, grow = row + (row >= 64 ? d2 : 0);
;             const float* s = x + (size_t)grow * DM;
;             if (MODE == 0) { s = src + (size_t)row * DM; if (MT == 3 && row >= 64) s = src2 + (size_t)(row - 64) * DM; }
;             ss[q] = 0.f;
; #pragma unroll
;             for (int i = 0; i < 4; ++i) { v[q][i] = *(const f32x4*)(s + i * 256 + lane * 4); ss[q] += v[q][i][0] * v[q][i][0] + v[q][i][1] * v[q][i][1] + v[q][i][2] * v[q][i][2] + v[q][i][3] * v[q][i][3]; }
;         }
; #pragma unroll
;         for (int o = 32; o >= 1; o >>= 1)
; #pragma unroll
;             for (int q = 0; q < 4; ++q) ss[q] += __shfl_xor(ss[q], o);
; #pragma unroll
;         for (int q = 0; q < 4; ++q) {
;             const int row = wave * (MT * 4) + rb * 4 + q, grow = row + (row >= 64 ? d2 : 0);
;             const float rstd = rsqrtf(ss[q] * (1.f / DM) + 1e-6f);
; #pragma unroll
;             for (int i = 0; i < 4; ++i) {
;                 if (MODE == 0) *(f32x4*)(x + (size_t)grow * DM + i * 256 + lane * 4) = v[q][i];
;                 if (MODE == 2) { f32x4 gg = *(const f32x4*)(g + i * 256 + lane * 4); *(f32x4*)(x + (size_t)grow * DM + i * 256 + lane * 4) = v[q][i] * rstd * gg; }
;                 else { u32x2 o = {pk2(v[q][i][0] * rstd, v[q][i][1] * rstd), pk2(v[q][i][2] * rstd, v[q][i][3] * rstd)}; *(u32x2*)(xb + (size_t)grow * DM + i * 256 + lane * 4) = o; }
;             }
;         }
	v_mov_b32_e32 v32, v23
	s_waitcnt vmcnt(0)
	v_mov_b32_e32 v33, v15
	v_mov_b32_e32 v30, v22
	v_mov_b32_e32 v31, v14
	v_pk_mul_f32 v[32:33], v[32:33], v[32:33]
	s_nop 0
	v_pk_fma_f32 v[30:31], v[30:31], v[30:31], v[32:33]
	v_mov_b32_e32 v32, v24
	v_mov_b32_e32 v33, v16
	v_pk_fma_f32 v[30:31], v[32:33], v[32:33], v[30:31]
	v_mov_b32_e32 v32, v25
	v_mov_b32_e32 v33, v17
	v_pk_fma_f32 v[80:81], v[32:33], v[32:33], v[30:31]
	v_lshlrev_b64 v[30:31], 12, v[72:73]
	v_lshl_add_u64 v[58:59], v[68:69], 0, v[30:31]
	global_load_dwordx4 v[38:41], v[58:59], off
	global_load_dwordx4 v[30:33], v[58:59], off offset:1024
	s_waitcnt vmcnt(1)
	v_mov_b32_e32 v62, v39
	s_waitcnt vmcnt(0)
	v_mov_b32_e32 v63, v31
	v_mov_b32_e32 v60, v38
	v_mov_b32_e32 v61, v30
	v_pk_mul_f32 v[62:63], v[62:63], v[62:63]
	s_nop 0
	v_pk_fma_f32 v[60:61], v[60:61], v[60:61], v[62:63]
	v_mov_b32_e32 v62, v40
	v_mov_b32_e32 v63, v32
	v_pk_fma_f32 v[60:61], v[62:63], v[62:63], v[60:61]
	v_mov_b32_e32 v62, v41
	v_mov_b32_e32 v63, v33
	v_pk_fma_f32 v[86:87], v[62:63], v[62:63], v[60:61]
	global_load_dwordx4 v[62:65], v[58:59], off offset:2048
	s_nop 0
	global_load_dwordx4 v[58:61], v[58:59], off offset:3072
	s_waitcnt vmcnt(1)
	v_mov_b32_e32 v96, v63
	s_waitcnt vmcnt(0)
	v_mov_b32_e32 v97, v59
	v_mov_b32_e32 v94, v62
	v_mov_b32_e32 v95, v58
	v_pk_mul_f32 v[96:97], v[96:97], v[96:97]
	s_nop 0
	v_pk_fma_f32 v[94:95], v[94:95], v[94:95], v[96:97]
	v_mov_b32_e32 v96, v64
	v_mov_b32_e32 v97, v60
	v_pk_fma_f32 v[94:95], v[96:97], v[96:97], v[94:95]
	v_mov_b32_e32 v96, v65
	v_mov_b32_e32 v97, v61
	v_pk_fma_f32 v[94:95], v[96:97], v[96:97], v[94:95]
	v_mov_b32_e32 v96, v88
	v_mov_b32_e32 v97, v78
	v_mov_b32_e32 v78, v89
	v_pk_add_f32 v[78:79], v[96:97], v[78:79]
	v_mov_b32_e32 v88, v90
	v_mov_b32_e32 v89, v84
	v_pk_add_f32 v[78:79], v[78:79], v[88:89]
	v_mov_b32_e32 v84, v91
	v_pk_add_f32 v[78:79], v[78:79], v[84:85]
	ds_bpermute_b32 v85, v224, v79
	ds_bpermute_b32 v84, v224, v78
	v_add_u32_e32 v90, 8, v0
	v_ashrrev_i32_e32 v91, 31, v90
	s_waitcnt lgkmcnt(0)
	v_pk_add_f32 v[78:79], v[78:79], v[84:85]
	ds_bpermute_b32 v85, v228, v79
	ds_bpermute_b32 v84, v228, v78
	s_waitcnt lgkmcnt(0)
	v_pk_add_f32 v[78:79], v[78:79], v[84:85]
	ds_bpermute_b32 v85, v227, v79
	ds_bpermute_b32 v84, v227, v78
	s_waitcnt lgkmcnt(0)
	v_pk_add_f32 v[78:79], v[78:79], v[84:85]
	ds_bpermute_b32 v85, v226, v79
	ds_bpermute_b32 v84, v226, v78
	s_waitcnt lgkmcnt(0)
	v_pk_add_f32 v[78:79], v[78:79], v[84:85]
	ds_bpermute_b32 v85, v225, v79
	ds_bpermute_b32 v84, v225, v78
	s_waitcnt lgkmcnt(0)
	v_pk_add_f32 v[78:79], v[78:79], v[84:85]
	ds_bpermute_b32 v85, v223, v79
	ds_bpermute_b32 v84, v223, v78
	s_waitcnt lgkmcnt(0)
	v_pk_add_f32 v[78:79], v[78:79], v[84:85]
	s_nop 0
	v_pk_fma_f32 v[78:79], v[78:79], s[4:5], v[70:71] op_sel_hi:[1,0,0]
	s_nop 0
	v_mul_f32_e32 v84, 0x4b800000, v79
	v_cmp_gt_f32_e64 s[0:1], s3, v79
	v_cmp_gt_f32_e32 vcc, s3, v78
	s_nop 0
	v_cndmask_b32_e64 v79, v79, v84, s[0:1]
	v_rsq_f32_e32 v79, v79
	s_nop 0
	v_mul_f32_e32 v84, 0x45800000, v79
	v_cndmask_b32_e64 v84, v79, v84, s[0:1]
	v_pk_mul_f32 v[10:11], v[10:11], v[84:85] op_sel_hi:[1,0]
	v_pk_mul_f32 v[12:13], v[12:13], v[84:85] op_sel_hi:[1,0]
	v_cvt_pk_f16_f32 v10, v10, v11
	v_cvt_pk_f16_f32 v11, v12, v13
	global_store_dwordx2 v[92:93], v[10:11], off offset:512
	v_pk_mul_f32 v[10:11], v[34:35], v[84:85] op_sel_hi:[1,0]
	v_pk_mul_f32 v[12:13], v[36:37], v[84:85] op_sel_hi:[1,0]
	v_cvt_pk_f16_f32 v10, v10, v11
	v_cvt_pk_f16_f32 v11, v12, v13
	global_store_dwordx2 v[92:93], v[10:11], off offset:1024
	v_pk_mul_f32 v[10:11], v[26:27], v[84:85] op_sel_hi:[1,0]
	v_pk_mul_f32 v[12:13], v[28:29], v[84:85] op_sel_hi:[1,0]
	v_cvt_pk_f16_f32 v10, v10, v11
	v_cvt_pk_f16_f32 v11, v12, v13
	global_store_dwordx2 v[92:93], v[10:11], off offset:1536
	v_mul_f32_e32 v10, 0x4b800000, v78
	v_cndmask_b32_e32 v10, v78, v10, vcc
	v_rsq_f32_e32 v10, v10
	v_pk_mul_f32 v[18:19], v[18:19], v[84:85] op_sel_hi:[1,0]
	v_pk_mul_f32 v[20:21], v[20:21], v[84:85] op_sel_hi:[1,0]
	v_cvt_pk_f16_f32 v18, v18, v19
	v_mul_f32_e32 v11, 0x45800000, v10
	v_cvt_pk_f16_f32 v19, v20, v21
	v_cndmask_b32_e32 v10, v10, v11, vcc
	global_store_dwordx2 v[92:93], v[18:19], off
	v_lshlrev_b64 v[12:13], 11, v[74:75]
	v_pk_mul_f32 v[18:19], v[46:47], v[10:11] op_sel_hi:[1,0]
	v_pk_mul_f32 v[20:21], v[48:49], v[10:11] op_sel_hi:[1,0]
	v_lshl_add_u64 v[12:13], v[66:67], 0, v[12:13]
	v_cvt_pk_f16_f32 v18, v18, v19
	v_cvt_pk_f16_f32 v19, v20, v21
	global_store_dwordx2 v[12:13], v[18:19], off
	v_pk_mul_f32 v[18:19], v[42:43], v[10:11] op_sel_hi:[1,0]
	v_pk_mul_f32 v[20:21], v[44:45], v[10:11] op_sel_hi:[1,0]
	v_cvt_pk_f16_f32 v18, v18, v19
	v_cvt_pk_f16_f32 v19, v20, v21
	global_store_dwordx2 v[12:13], v[18:19], off offset:512
	v_pk_mul_f32 v[18:19], v[54:55], v[10:11] op_sel_hi:[1,0]
	v_pk_mul_f32 v[20:21], v[56:57], v[10:11] op_sel_hi:[1,0]
	v_cvt_pk_f16_f32 v18, v18, v19
	v_cvt_pk_f16_f32 v19, v20, v21
	global_store_dwordx2 v[12:13], v[18:19], off offset:1024
	v_pk_mul_f32 v[18:19], v[50:51], v[10:11] op_sel_hi:[1,0]
	v_pk_mul_f32 v[10:11], v[52:53], v[10:11] op_sel_hi:[1,0]
	v_cvt_pk_f16_f32 v18, v18, v19
	v_cvt_pk_f16_f32 v19, v10, v11
	global_store_dwordx2 v[12:13], v[18:19], off offset:1536
	v_mov_b32_e32 v12, v86
	v_mov_b32_e32 v13, v76
	v_mov_b32_e32 v76, v87
	v_pk_add_f32 v[12:13], v[12:13], v[76:77]
	v_mov_b32_e32 v18, v94
	v_mov_b32_e32 v19, v80
	v_pk_add_f32 v[12:13], v[12:13], v[18:19]
	v_mov_b32_e32 v80, v95
	v_pk_add_f32 v[12:13], v[12:13], v[80:81]
	ds_bpermute_b32 v19, v224, v13
	ds_bpermute_b32 v18, v224, v12
	v_lshlrev_b64 v[10:11], 11, v[82:83]
	v_lshl_add_u64 v[10:11], v[66:67], 0, v[10:11]
	v_add_u32_e32 v74, 9, v0
	v_ashrrev_i32_e32 v75, 31, v74
	s_waitcnt lgkmcnt(0)
; DI unsigned pk2(float lo, float hi) { f32x2 v = {lo, hi}; bf2_t b = __builtin_convertvector(v, bf2_t); return __builtin_bit_cast(unsigned, b); }
; template <int MODE, int MT> DI void norm_rows(const float* src, const float* src2, float* x, int d2, bf16_t* xb, const float* __restrict__ g) {
;     ...
;     for (int rb = 0; rb < MT; ++rb) {
;         f32x4 v[4][4]; float ss[4];
; #pragma unroll
;         for (int q = 0; q < 4; ++q) {
;             const int row = wave * (MT * 4) + rb * 4 + q, grow = row + (row >= 64 ? d2 : 0);
;             const float* s = x + (size_t)grow * DM;
;             if (MODE == 0) { s = src + (size_t)row * DM; if (MT == 3 && row >= 64) s = src2 + (size_t)(row - 64) * DM; }
;             ss[q] = 0.f;
; #pragma unroll
;             for (int i = 0; i < 4; ++i) { v[q][i] = *(const f32x4*)(s + i * 256 + lane * 4); ss[q] += v[q][i][0] * v[q][i][0] + v[q][i][1] * v[q][i][1] + v[q][i][2] * v[q][i][2] + v[q][i][3] * v[q][i][3]; }
;         }
; #pragma unroll
;         for (int o = 32; o >= 1; o >>= 1)
; #pragma unroll
;             for (int q = 0; q < 4; ++q) ss[q] += __shfl_xor(ss[q], o);
; #pragma unroll
;         for (int q = 0; q < 4; ++q) {
;             const int row = wave * (MT * 4) + rb * 4 + q, grow = row + (row >= 64 ? d2 : 0);
;             const float rstd = rsqrtf(ss[q] * (1.f / DM) + 1e-6f);
; #pragma unroll
;             for (int i = 0; i < 4; ++i) {
;                 if (MODE == 0) *(f32x4*)(x + (size_t)grow * DM + i * 256 + lane * 4) = v[q][i];
;                 if (MODE == 2) { f32x4 gg = *(const f32x4*)(g + i * 256 + lane * 4); *(f32x4*)(x + (size_t)grow * DM + i * 256 + lane * 4) = v[q][i] * rstd * gg; }
;                 else { u32x2 o = {pk2(v[q][i][0] * rstd, v[q][i][1] * rstd), pk2(v[q][i][2] * rstd, v[q][i][3] * rstd)}; *(u32x2*)(xb + (size_t)grow * DM + i * 256 + lane * 4) = o; }
;             }
;         }
	v_pk_add_f32 v[12:13], v[12:13], v[18:19]
	ds_bpermute_b32 v19, v228, v13
	ds_bpermute_b32 v18, v228, v12
	v_add_u32_e32 v82, 10, v0
	v_ashrrev_i32_e32 v83, 31, v82
	s_waitcnt lgkmcnt(0)
	v_pk_add_f32 v[12:13], v[12:13], v[18:19]
	ds_bpermute_b32 v19, v227, v13
	ds_bpermute_b32 v18, v227, v12
	s_waitcnt lgkmcnt(0)
	v_pk_add_f32 v[12:13], v[12:13], v[18:19]
	ds_bpermute_b32 v19, v226, v13
	ds_bpermute_b32 v18, v226, v12
	s_waitcnt lgkmcnt(0)
	v_pk_add_f32 v[12:13], v[12:13], v[18:19]
	ds_bpermute_b32 v19, v225, v13
	ds_bpermute_b32 v18, v225, v12
	s_waitcnt lgkmcnt(0)
	v_pk_add_f32 v[12:13], v[12:13], v[18:19]
	ds_bpermute_b32 v19, v223, v13
	ds_bpermute_b32 v18, v223, v12
	s_waitcnt lgkmcnt(0)
	v_pk_add_f32 v[12:13], v[12:13], v[18:19]
	s_nop 0
	v_pk_fma_f32 v[12:13], v[12:13], s[4:5], v[70:71] op_sel_hi:[1,0,0]
	s_nop 0
	v_mul_f32_e32 v18, 0x4b800000, v13
	v_cmp_gt_f32_e64 s[0:1], s3, v13
	v_cmp_gt_f32_e32 vcc, s3, v12
	s_nop 0
	v_cndmask_b32_e64 v13, v13, v18, s[0:1]
	v_rsq_f32_e32 v13, v13
	s_nop 0
	v_mul_f32_e32 v18, 0x45800000, v13
	v_cndmask_b32_e64 v18, v13, v18, s[0:1]
	v_pk_mul_f32 v[2:3], v[2:3], v[18:19] op_sel_hi:[1,0]
	v_pk_mul_f32 v[4:5], v[4:5], v[18:19] op_sel_hi:[1,0]
	v_cvt_pk_f16_f32 v2, v2, v3
	v_cvt_pk_f16_f32 v3, v4, v5
	global_store_dwordx2 v[10:11], v[2:3], off offset:512
	v_pk_mul_f32 v[2:3], v[22:23], v[18:19] op_sel_hi:[1,0]
	v_pk_mul_f32 v[4:5], v[24:25], v[18:19] op_sel_hi:[1,0]
	v_cvt_pk_f16_f32 v2, v2, v3
	v_cvt_pk_f16_f32 v3, v4, v5
	global_store_dwordx2 v[10:11], v[2:3], off offset:1024
	v_pk_mul_f32 v[2:3], v[14:15], v[18:19] op_sel_hi:[1,0]
	v_pk_mul_f32 v[4:5], v[16:17], v[18:19] op_sel_hi:[1,0]
	v_cvt_pk_f16_f32 v2, v2, v3
	v_cvt_pk_f16_f32 v3, v4, v5
	global_store_dwordx2 v[10:11], v[2:3], off offset:1536
	v_mul_f32_e32 v2, 0x4b800000, v12
	v_cndmask_b32_e32 v2, v12, v2, vcc
	v_rsq_f32_e32 v2, v2
	v_pk_mul_f32 v[6:7], v[6:7], v[18:19] op_sel_hi:[1,0]
	v_pk_mul_f32 v[8:9], v[8:9], v[18:19] op_sel_hi:[1,0]
	v_cvt_pk_f16_f32 v6, v6, v7
	v_mul_f32_e32 v3, 0x45800000, v2
	v_cvt_pk_f16_f32 v7, v8, v9
	v_cndmask_b32_e32 v2, v2, v3, vcc
	global_store_dwordx2 v[10:11], v[6:7], off
	v_lshlrev_b64 v[4:5], 11, v[72:73]
	v_pk_mul_f32 v[6:7], v[38:39], v[2:3] op_sel_hi:[1,0]
	v_pk_mul_f32 v[8:9], v[40:41], v[2:3] op_sel_hi:[1,0]
	v_lshl_add_u64 v[4:5], v[66:67], 0, v[4:5]
	v_cvt_pk_f16_f32 v6, v6, v7
	v_cvt_pk_f16_f32 v7, v8, v9
	global_store_dwordx2 v[4:5], v[6:7], off
	v_pk_mul_f32 v[6:7], v[30:31], v[2:3] op_sel_hi:[1,0]
	v_pk_mul_f32 v[8:9], v[32:33], v[2:3] op_sel_hi:[1,0]
	v_cvt_pk_f16_f32 v6, v6, v7
	v_cvt_pk_f16_f32 v7, v8, v9
	global_store_dwordx2 v[4:5], v[6:7], off offset:512
	v_pk_mul_f32 v[6:7], v[62:63], v[2:3] op_sel_hi:[1,0]
	v_pk_mul_f32 v[8:9], v[64:65], v[2:3] op_sel_hi:[1,0]
	v_cvt_pk_f16_f32 v6, v6, v7
	v_cvt_pk_f16_f32 v7, v8, v9
	global_store_dwordx2 v[4:5], v[6:7], off offset:1024
	v_pk_mul_f32 v[6:7], v[58:59], v[2:3] op_sel_hi:[1,0]
	v_pk_mul_f32 v[2:3], v[60:61], v[2:3] op_sel_hi:[1,0]
	v_cvt_pk_f16_f32 v6, v6, v7
	v_cvt_pk_f16_f32 v7, v2, v3
	v_lshlrev_b64 v[2:3], 12, v[90:91]
	global_store_dwordx2 v[4:5], v[6:7], off offset:1536
	v_lshl_add_u64 v[2:3], v[68:69], 0, v[2:3]
	global_load_dwordx4 v[18:21], v[2:3], off
	global_load_dwordx4 v[10:13], v[2:3], off offset:1024
	global_load_dwordx4 v[34:37], v[2:3], off offset:2048
	global_load_dwordx4 v[26:29], v[2:3], off offset:3072
	v_add_u32_e32 v72, 11, v0
	v_ashrrev_i32_e32 v73, 31, v72
	v_lshlrev_b64 v[90:91], 11, v[90:91]
	v_lshl_add_u64 v[90:91], v[66:67], 0, v[90:91]
	s_waitcnt vmcnt(3)
	v_mov_b32_e32 v6, v19
	s_waitcnt vmcnt(2)
	v_mov_b32_e32 v7, v11
	v_mov_b32_e32 v4, v18
	v_mov_b32_e32 v5, v10
	v_pk_mul_f32 v[6:7], v[6:7], v[6:7]
	s_waitcnt vmcnt(1)
	v_mov_b32_e32 v2, v34
	v_pk_fma_f32 v[4:5], v[4:5], v[4:5], v[6:7]
	v_mov_b32_e32 v6, v20
	v_mov_b32_e32 v7, v12
	v_pk_fma_f32 v[4:5], v[6:7], v[6:7], v[4:5]
	v_mov_b32_e32 v6, v21
	v_mov_b32_e32 v7, v13
	v_pk_fma_f32 v[78:79], v[6:7], v[6:7], v[4:5]
	v_mov_b32_e32 v4, v35
	s_waitcnt vmcnt(0)
	v_mov_b32_e32 v5, v27
	v_mov_b32_e32 v3, v26
	v_pk_mul_f32 v[4:5], v[4:5], v[4:5]
	s_nop 0
	v_pk_fma_f32 v[2:3], v[2:3], v[2:3], v[4:5]
	v_mov_b32_e32 v4, v36
	v_mov_b32_e32 v5, v28
	v_pk_fma_f32 v[2:3], v[4:5], v[4:5], v[2:3]
	v_mov_b32_e32 v4, v37
	v_mov_b32_e32 v5, v29
	v_pk_fma_f32 v[84:85], v[4:5], v[4:5], v[2:3]
	v_lshlrev_b64 v[2:3], 12, v[74:75]
	v_lshl_add_u64 v[2:3], v[68:69], 0, v[2:3]
	global_load_dwordx4 v[46:49], v[2:3], off
	global_load_dwordx4 v[42:45], v[2:3], off offset:1024
	global_load_dwordx4 v[54:57], v[2:3], off offset:2048
	global_load_dwordx4 v[50:53], v[2:3], off offset:3072
	s_waitcnt vmcnt(3)
	v_mov_b32_e32 v6, v47
	s_waitcnt vmcnt(2)
	v_mov_b32_e32 v7, v43
	v_mov_b32_e32 v4, v46
	v_mov_b32_e32 v5, v42
	v_pk_mul_f32 v[6:7], v[6:7], v[6:7]
	s_waitcnt vmcnt(1)
	v_mov_b32_e32 v2, v54
	v_pk_fma_f32 v[4:5], v[4:5], v[4:5], v[6:7]
	v_mov_b32_e32 v6, v48
	v_mov_b32_e32 v7, v44
	v_pk_fma_f32 v[4:5], v[6:7], v[6:7], v[4:5]
	v_mov_b32_e32 v6, v49
	v_mov_b32_e32 v7, v45
	v_pk_fma_f32 v[86:87], v[6:7], v[6:7], v[4:5]
	v_mov_b32_e32 v4, v55
	s_waitcnt vmcnt(0)
	v_mov_b32_e32 v5, v51
	v_mov_b32_e32 v3, v50
	v_pk_mul_f32 v[4:5], v[4:5], v[4:5]
	s_nop 0
	v_pk_fma_f32 v[2:3], v[2:3], v[2:3], v[4:5]
	v_mov_b32_e32 v4, v56
	v_mov_b32_e32 v5, v52
	v_pk_fma_f32 v[2:3], v[4:5], v[4:5], v[2:3]
	v_mov_b32_e32 v4, v57
	v_mov_b32_e32 v5, v53
	v_pk_fma_f32 v[88:89], v[4:5], v[4:5], v[2:3]
	v_lshlrev_b64 v[2:3], 12, v[82:83]
	v_lshl_add_u64 v[14:15], v[68:69], 0, v[2:3]
	global_load_dwordx4 v[6:9], v[14:15], off
	global_load_dwordx4 v[2:5], v[14:15], off offset:1024
	s_waitcnt vmcnt(1)
; DI unsigned pk2(float lo, float hi) { f32x2 v = {lo, hi}; bf2_t b = __builtin_convertvector(v, bf2_t); return __builtin_bit_cast(unsigned, b); }
; template <int MODE, int MT> DI void norm_rows(const float* src, const float* src2, float* x, int d2, bf16_t* xb, const float* __restrict__ g) {
;     ...
;     for (int rb = 0; rb < MT; ++rb) {
;         f32x4 v[4][4]; float ss[4];
; #pragma unroll
;         for (int q = 0; q < 4; ++q) {
;             const int row = wave * (MT * 4) + rb * 4 + q, grow = row + (row >= 64 ? d2 : 0);
;             const float* s = x + (size_t)grow * DM;
;             if (MODE == 0) { s = src + (size_t)row * DM; if (MT == 3 && row >= 64) s = src2 + (size_t)(row - 64) * DM; }
;             ss[q] = 0.f;
; #pragma unroll
;             for (int i = 0; i < 4; ++i) { v[q][i] = *(const f32x4*)(s + i * 256 + lane * 4); ss[q] += v[q][i][0] * v[q][i][0] + v[q][i][1] * v[q][i][1] + v[q][i][2] * v[q][i][2] + v[q][i][3] * v[q][i][3]; }
;         }
; #pragma unroll
;         for (int o = 32; o >= 1; o >>= 1)
; #pragma unroll
;             for (int q = 0; q < 4; ++q) ss[q] += __shfl_xor(ss[q], o);
; #pragma unroll
;         for (int q = 0; q < 4; ++q) {
;             const int row = wave * (MT * 4) + rb * 4 + q, grow = row + (row >= 64 ? d2 : 0);
;             const float rstd = rsqrtf(ss[q] * (1.f / DM) + 1e-6f);
; #pragma unroll
;             for (int i = 0; i < 4; ++i) {
;                 if (MODE == 0) *(f32x4*)(x + (size_t)grow * DM + i * 256 + lane * 4) = v[q][i];
;                 if (MODE == 2) { f32x4 gg = *(const f32x4*)(g + i * 256 + lane * 4); *(f32x4*)(x + (size_t)grow * DM + i * 256 + lane * 4) = v[q][i] * rstd * gg; }
;                 else { u32x2 o = {pk2(v[q][i][0] * rstd, v[q][i][1] * rstd), pk2(v[q][i][2] * rstd, v[q][i][3] * rstd)}; *(u32x2*)(xb + (size_t)grow * DM + i * 256 + lane * 4) = o; }
;             }
;         }
	v_mov_b32_e32 v22, v7
	s_waitcnt vmcnt(0)
	v_mov_b32_e32 v23, v3
	v_mov_b32_e32 v16, v6
	v_mov_b32_e32 v17, v2
	v_pk_mul_f32 v[22:23], v[22:23], v[22:23]
	s_nop 0
	v_pk_fma_f32 v[16:17], v[16:17], v[16:17], v[22:23]
	v_mov_b32_e32 v22, v8
	v_mov_b32_e32 v23, v4
	v_pk_fma_f32 v[16:17], v[22:23], v[22:23], v[16:17]
	v_mov_b32_e32 v22, v9
	v_mov_b32_e32 v23, v5
	v_pk_fma_f32 v[76:77], v[22:23], v[22:23], v[16:17]
	global_load_dwordx4 v[22:25], v[14:15], off offset:2048
	s_nop 0
	global_load_dwordx4 v[14:17], v[14:15], off offset:3072
	s_waitcnt vmcnt(1)
	v_mov_b32_e32 v32, v23
	s_waitcnt vmcnt(0)
	v_mov_b32_e32 v33, v15
	v_mov_b32_e32 v30, v22
	v_mov_b32_e32 v31, v14
	v_pk_mul_f32 v[32:33], v[32:33], v[32:33]
	s_nop 0
	v_pk_fma_f32 v[30:31], v[30:31], v[30:31], v[32:33]
	v_mov_b32_e32 v32, v24
	v_mov_b32_e32 v33, v16
	v_pk_fma_f32 v[30:31], v[32:33], v[32:33], v[30:31]
	v_mov_b32_e32 v32, v25
	v_mov_b32_e32 v33, v17
	v_pk_fma_f32 v[80:81], v[32:33], v[32:33], v[30:31]
	v_lshlrev_b64 v[30:31], 12, v[72:73]
	v_lshl_add_u64 v[58:59], v[68:69], 0, v[30:31]
	global_load_dwordx4 v[38:41], v[58:59], off
	global_load_dwordx4 v[30:33], v[58:59], off offset:1024
	s_waitcnt vmcnt(1)
	v_mov_b32_e32 v62, v39
	s_waitcnt vmcnt(0)
	v_mov_b32_e32 v63, v31
	v_mov_b32_e32 v60, v38
	v_mov_b32_e32 v61, v30
	v_pk_mul_f32 v[62:63], v[62:63], v[62:63]
	s_nop 0
	v_pk_fma_f32 v[60:61], v[60:61], v[60:61], v[62:63]
	v_mov_b32_e32 v62, v40
	v_mov_b32_e32 v63, v32
	v_pk_fma_f32 v[60:61], v[62:63], v[62:63], v[60:61]
	v_mov_b32_e32 v62, v41
	v_mov_b32_e32 v63, v33
	v_pk_fma_f32 v[68:69], v[62:63], v[62:63], v[60:61]
	global_load_dwordx4 v[62:65], v[58:59], off offset:2048
	s_nop 0
	global_load_dwordx4 v[58:61], v[58:59], off offset:3072
	s_waitcnt vmcnt(1)
	v_mov_b32_e32 v94, v63
	s_waitcnt vmcnt(0)
	v_mov_b32_e32 v95, v59
	v_mov_b32_e32 v92, v62
	v_mov_b32_e32 v93, v58
	v_pk_mul_f32 v[94:95], v[94:95], v[94:95]
	s_nop 0
	v_pk_fma_f32 v[92:93], v[92:93], v[92:93], v[94:95]
	v_mov_b32_e32 v94, v64
	v_mov_b32_e32 v95, v60
	v_pk_fma_f32 v[92:93], v[94:95], v[94:95], v[92:93]
	v_mov_b32_e32 v94, v65
	v_mov_b32_e32 v95, v61
	v_pk_fma_f32 v[92:93], v[94:95], v[94:95], v[92:93]
	v_mov_b32_e32 v94, v86
	v_mov_b32_e32 v95, v78
	v_mov_b32_e32 v78, v87
	v_pk_add_f32 v[78:79], v[94:95], v[78:79]
	v_mov_b32_e32 v86, v88
	v_mov_b32_e32 v87, v84
	v_pk_add_f32 v[78:79], v[78:79], v[86:87]
	v_mov_b32_e32 v84, v89
	v_pk_add_f32 v[78:79], v[78:79], v[84:85]
	ds_bpermute_b32 v85, v224, v79
	ds_bpermute_b32 v84, v224, v78
	s_waitcnt lgkmcnt(0)
	v_pk_add_f32 v[78:79], v[78:79], v[84:85]
	ds_bpermute_b32 v85, v228, v79
	ds_bpermute_b32 v84, v228, v78
	s_waitcnt lgkmcnt(0)
	v_pk_add_f32 v[78:79], v[78:79], v[84:85]
	ds_bpermute_b32 v85, v227, v79
	ds_bpermute_b32 v84, v227, v78
	s_waitcnt lgkmcnt(0)
	v_pk_add_f32 v[78:79], v[78:79], v[84:85]
	ds_bpermute_b32 v85, v226, v79
	ds_bpermute_b32 v84, v226, v78
	s_waitcnt lgkmcnt(0)
	v_pk_add_f32 v[78:79], v[78:79], v[84:85]
	ds_bpermute_b32 v85, v225, v79
	ds_bpermute_b32 v84, v225, v78
	s_waitcnt lgkmcnt(0)
	v_pk_add_f32 v[78:79], v[78:79], v[84:85]
	ds_bpermute_b32 v85, v223, v79
	ds_bpermute_b32 v84, v223, v78
	s_waitcnt lgkmcnt(0)
	v_pk_add_f32 v[78:79], v[78:79], v[84:85]
	s_nop 0
	v_pk_fma_f32 v[78:79], v[78:79], s[4:5], v[70:71] op_sel_hi:[1,0,0]
	s_nop 0
	v_mul_f32_e32 v0, 0x4b800000, v79
	v_cmp_gt_f32_e64 s[0:1], s3, v79
	v_cmp_gt_f32_e32 vcc, s3, v78
	s_nop 0
	v_cndmask_b32_e64 v0, v79, v0, s[0:1]
	v_rsq_f32_e32 v0, v0
	s_nop 0
	v_mul_f32_e32 v79, 0x45800000, v0
	v_cndmask_b32_e64 v0, v0, v79, s[0:1]
	v_pk_mul_f32 v[10:11], v[10:11], v[0:1] op_sel_hi:[1,0]
	v_pk_mul_f32 v[12:13], v[12:13], v[0:1] op_sel_hi:[1,0]
	v_cvt_pk_f16_f32 v10, v10, v11
	v_cvt_pk_f16_f32 v11, v12, v13
	global_store_dwordx2 v[90:91], v[10:11], off offset:512
	v_pk_mul_f32 v[10:11], v[34:35], v[0:1] op_sel_hi:[1,0]
	v_pk_mul_f32 v[12:13], v[36:37], v[0:1] op_sel_hi:[1,0]
	v_cvt_pk_f16_f32 v10, v10, v11
	v_cvt_pk_f16_f32 v11, v12, v13
	v_pk_mul_f32 v[18:19], v[18:19], v[0:1] op_sel_hi:[1,0]
	v_pk_mul_f32 v[20:21], v[20:21], v[0:1] op_sel_hi:[1,0]
	global_store_dwordx2 v[90:91], v[10:11], off offset:1024
	v_pk_mul_f32 v[10:11], v[26:27], v[0:1] op_sel_hi:[1,0]
	v_pk_mul_f32 v[12:13], v[28:29], v[0:1] op_sel_hi:[1,0]
	v_mul_f32_e32 v0, 0x4b800000, v78
	v_cndmask_b32_e32 v0, v78, v0, vcc
	v_rsq_f32_e32 v0, v0
	v_cvt_pk_f16_f32 v10, v10, v11
	v_cvt_pk_f16_f32 v11, v12, v13
	global_store_dwordx2 v[90:91], v[10:11], off offset:1536
	v_mul_f32_e32 v10, 0x45800000, v0
	v_cvt_pk_f16_f32 v18, v18, v19
	v_cvt_pk_f16_f32 v19, v20, v21
	v_cndmask_b32_e32 v0, v0, v10, vcc
	global_store_dwordx2 v[90:91], v[18:19], off
	v_lshlrev_b64 v[10:11], 11, v[74:75]
	v_pk_mul_f32 v[12:13], v[46:47], v[0:1] op_sel_hi:[1,0]
	v_pk_mul_f32 v[18:19], v[48:49], v[0:1] op_sel_hi:[1,0]
	v_lshl_add_u64 v[10:11], v[66:67], 0, v[10:11]
	v_cvt_pk_f16_f32 v12, v12, v13
	v_cvt_pk_f16_f32 v13, v18, v19
	global_store_dwordx2 v[10:11], v[12:13], off
	v_pk_mul_f32 v[12:13], v[42:43], v[0:1] op_sel_hi:[1,0]
	v_pk_mul_f32 v[18:19], v[44:45], v[0:1] op_sel_hi:[1,0]
	v_cvt_pk_f16_f32 v12, v12, v13
	v_cvt_pk_f16_f32 v13, v18, v19
	global_store_dwordx2 v[10:11], v[12:13], off offset:512
	v_pk_mul_f32 v[12:13], v[54:55], v[0:1] op_sel_hi:[1,0]
	v_pk_mul_f32 v[18:19], v[56:57], v[0:1] op_sel_hi:[1,0]
	v_cvt_pk_f16_f32 v12, v12, v13
	v_cvt_pk_f16_f32 v13, v18, v19
	global_store_dwordx2 v[10:11], v[12:13], off offset:1024
	v_pk_mul_f32 v[12:13], v[50:51], v[0:1] op_sel_hi:[1,0]
	v_pk_mul_f32 v[18:19], v[52:53], v[0:1] op_sel_hi:[1,0]
	v_cvt_pk_f16_f32 v12, v12, v13
	v_cvt_pk_f16_f32 v13, v18, v19
	global_store_dwordx2 v[10:11], v[12:13], off offset:1536
	v_mov_b32_e32 v12, v68
	v_mov_b32_e32 v13, v76
	v_mov_b32_e32 v76, v69
	v_pk_add_f32 v[12:13], v[12:13], v[76:77]
	v_mov_b32_e32 v18, v92
	v_mov_b32_e32 v19, v80
	v_pk_add_f32 v[12:13], v[12:13], v[18:19]
	v_mov_b32_e32 v80, v93
	v_pk_add_f32 v[12:13], v[12:13], v[80:81]
	ds_bpermute_b32 v19, v224, v13
	ds_bpermute_b32 v18, v224, v12
	v_lshlrev_b64 v[10:11], 11, v[82:83]
	v_lshl_add_u64 v[10:11], v[66:67], 0, v[10:11]
	s_waitcnt lgkmcnt(0)
; DI int otid() { int t = threadIdx.x; asm volatile("" : "+v"(t)); return t; }
; template <int MODE, int MT> DI void norm_rows(const float* src, const float* src2, float* x, int d2, bf16_t* xb, const float* __restrict__ g) {
;     ...
; #pragma unroll
;         for (int q = 0; q < 4; ++q) {
;             const int row = wave * (MT * 4) + rb * 4 + q, grow = row + (row >= 64 ? d2 : 0);
;             const float rstd = rsqrtf(ss[q] * (1.f / DM) + 1e-6f);
; #pragma unroll
;             for (int i = 0; i < 4; ++i) {
;                 if (MODE == 0) *(f32x4*)(x + (size_t)grow * DM + i * 256 + lane * 4) = v[q][i];
;                 if (MODE == 2) { f32x4 gg = *(const f32x4*)(g + i * 256 + lane * 4); *(f32x4*)(x + (size_t)grow * DM + i * 256 + lane * 4) = v[q][i] * rstd * gg; }
;                 else { u32x2 o = {pk2(v[q][i][0] * rstd, v[q][i][1] * rstd), pk2(v[q][i][2] * rstd, v[q][i][3] * rstd)}; *(u32x2*)(xb + (size_t)grow * DM + i * 256 + lane * 4) = o; }
;             }
;         }
;     ...
;     constexpr int KS = K / 16, NCH = K / A_CHUNK, PD = 4;
;     const int tid = otid(), wave = tid >> 6, lane = tid & 63, r = lane & 31, h = lane >> 5;
;     const u32x4* Bw = (const u32x4*)Wp;
; #pragma unroll 1
;     for (int pass = 0; pass * NWAVE < NU; ++pass) {
;         const int unit = pass * NWAVE + wave;
;         const bool active = unit < NU;
;         const int ucl = active ? unit : NU - 1;
;         const u32x4* bp = Bw + (size_t)(ucl * NT) * 64 + lane;
;         const size_t kstr = (size_t)NU * NT * 64;
;         f32x16 acc[MT][NT];
; #pragma unroll
;         for (int mi = 0; mi < MT; ++mi)
; #pragma unroll
;             for (int nj = 0; nj < NT; ++nj)
; #pragma unroll
;                 for (int i = 0; i < 16; ++i) acc[mi][nj][i] = 0.f;
;         u32x4 bq[PD][NT];
; #pragma unroll
;         for (int s = 0; s < PD; ++s)
; #pragma unroll
;             for (int j = 0; j < NT; ++j) bq[s][j] = bp[(size_t)s * kstr + j * 64];
;         u32x4 areg[MT];
;         if (pass == 0) __syncthreads();
; #pragma unroll
;         for (int i = 0; i < MT; ++i) { const int idx = i * NTHR + tid, row = idx >> 4, seg = idx & 15; areg[i] = *(const u32x4*)(A + ((row + (i == 2 ? d2 : 0)) * lda + seg * 8)); }
; #pragma unroll
;         for (int i = 0; i < MT; ++i) { const int idx = i * NTHR + tid, row = idx >> 4, seg = idx & 15; *(u32x4*)(lds + row * A_LD + seg * 16) = areg[i]; }
;         lds_barrier();
	v_pk_add_f32 v[12:13], v[12:13], v[18:19]
	ds_bpermute_b32 v19, v228, v13
	ds_bpermute_b32 v18, v228, v12
	s_waitcnt lgkmcnt(0)
	v_pk_add_f32 v[12:13], v[12:13], v[18:19]
	ds_bpermute_b32 v19, v227, v13
	ds_bpermute_b32 v18, v227, v12
	s_waitcnt lgkmcnt(0)
	v_pk_add_f32 v[12:13], v[12:13], v[18:19]
	ds_bpermute_b32 v19, v226, v13
	ds_bpermute_b32 v18, v226, v12
	s_waitcnt lgkmcnt(0)
	v_pk_add_f32 v[12:13], v[12:13], v[18:19]
	ds_bpermute_b32 v19, v225, v13
	ds_bpermute_b32 v18, v225, v12
	s_waitcnt lgkmcnt(0)
	v_pk_add_f32 v[12:13], v[12:13], v[18:19]
	ds_bpermute_b32 v19, v223, v13
	ds_bpermute_b32 v18, v223, v12
	s_waitcnt lgkmcnt(0)
	v_pk_add_f32 v[12:13], v[12:13], v[18:19]
	s_nop 0
	v_pk_fma_f32 v[12:13], v[12:13], s[4:5], v[70:71] op_sel_hi:[1,0,0]
	s_nop 0
	v_mul_f32_e32 v0, 0x4b800000, v13
	v_cmp_gt_f32_e64 s[0:1], s3, v13
	v_cmp_gt_f32_e32 vcc, s3, v12
	v_readlane_b32 s3, v252, 45
	v_cndmask_b32_e64 v0, v13, v0, s[0:1]
	v_rsq_f32_e32 v0, v0
	s_nop 0
	v_mul_f32_e32 v13, 0x45800000, v0
	v_cndmask_b32_e64 v0, v0, v13, s[0:1]
	v_pk_mul_f32 v[2:3], v[2:3], v[0:1] op_sel_hi:[1,0]
	v_pk_mul_f32 v[4:5], v[4:5], v[0:1] op_sel_hi:[1,0]
	v_cvt_pk_f16_f32 v2, v2, v3
	v_cvt_pk_f16_f32 v3, v4, v5
	global_store_dwordx2 v[10:11], v[2:3], off offset:512
	v_pk_mul_f32 v[2:3], v[22:23], v[0:1] op_sel_hi:[1,0]
	v_pk_mul_f32 v[4:5], v[24:25], v[0:1] op_sel_hi:[1,0]
	v_cvt_pk_f16_f32 v2, v2, v3
	v_cvt_pk_f16_f32 v3, v4, v5
	v_pk_mul_f32 v[6:7], v[6:7], v[0:1] op_sel_hi:[1,0]
	v_pk_mul_f32 v[8:9], v[8:9], v[0:1] op_sel_hi:[1,0]
	global_store_dwordx2 v[10:11], v[2:3], off offset:1024
	v_pk_mul_f32 v[2:3], v[14:15], v[0:1] op_sel_hi:[1,0]
	v_pk_mul_f32 v[4:5], v[16:17], v[0:1] op_sel_hi:[1,0]
	v_mul_f32_e32 v0, 0x4b800000, v12
	v_cndmask_b32_e32 v0, v12, v0, vcc
	v_rsq_f32_e32 v0, v0
	v_cvt_pk_f16_f32 v2, v2, v3
	v_cvt_pk_f16_f32 v3, v4, v5
	global_store_dwordx2 v[10:11], v[2:3], off offset:1536
	v_mul_f32_e32 v2, 0x45800000, v0
	v_cvt_pk_f16_f32 v6, v6, v7
	v_cvt_pk_f16_f32 v7, v8, v9
	v_cndmask_b32_e32 v0, v0, v2, vcc
	global_store_dwordx2 v[10:11], v[6:7], off
	v_lshlrev_b64 v[2:3], 11, v[72:73]
	v_pk_mul_f32 v[4:5], v[38:39], v[0:1] op_sel_hi:[1,0]
	v_pk_mul_f32 v[6:7], v[40:41], v[0:1] op_sel_hi:[1,0]
	v_lshl_add_u64 v[2:3], v[66:67], 0, v[2:3]
	v_cvt_pk_f16_f32 v4, v4, v5
	v_cvt_pk_f16_f32 v5, v6, v7
	global_store_dwordx2 v[2:3], v[4:5], off
	v_pk_mul_f32 v[4:5], v[30:31], v[0:1] op_sel_hi:[1,0]
	v_pk_mul_f32 v[6:7], v[32:33], v[0:1] op_sel_hi:[1,0]
	v_cvt_pk_f16_f32 v4, v4, v5
	v_cvt_pk_f16_f32 v5, v6, v7
	global_store_dwordx2 v[2:3], v[4:5], off offset:512
	v_pk_mul_f32 v[4:5], v[62:63], v[0:1] op_sel_hi:[1,0]
	v_pk_mul_f32 v[6:7], v[64:65], v[0:1] op_sel_hi:[1,0]
	v_cvt_pk_f16_f32 v4, v4, v5
	v_cvt_pk_f16_f32 v5, v6, v7
	s_mul_i32 s1, s73, 0xb000
	global_store_dwordx2 v[2:3], v[4:5], off offset:1024
	v_pk_mul_f32 v[4:5], v[58:59], v[0:1] op_sel_hi:[1,0]
	v_pk_mul_f32 v[6:7], v[60:61], v[0:1] op_sel_hi:[1,0]
	s_mul_hi_i32 s0, s73, 0xb000
	s_add_u32 s8, s3, s1
	v_readlane_b32 s1, v252, 46
	v_cvt_pk_f16_f32 v4, v4, v5
	v_cvt_pk_f16_f32 v5, v6, v7
	s_addc_u32 s9, s1, s0
	s_mul_hi_i32 s0, s74, 0xb000
	s_mul_i32 s74, s74, 0xb000
	v_readlane_b32 s1, v255, 46
	v_mov_b32_e32 v0, v176
	global_store_dwordx2 v[2:3], v[4:5], off offset:1536
	s_add_u32 s28, s1, s74
	v_readlane_b32 s1, v255, 47
	s_addc_u32 s29, s1, s0
	v_lshlrev_b32_e32 v5, 3, v0
	v_and_b32_e32 v2, 63, v0
	v_readlane_b32 s0, v255, 44
	v_and_b32_e32 v10, 0x78, v5
	v_lshlrev_b32_e32 v5, 4, v0
	v_lshlrev_b32_e32 v2, 4, v2
	v_mov_b32_e32 v3, v1
	v_readlane_b32 s1, v255, 45
	v_and_b32_e32 v224, 0xf0, v5
	v_lshrrev_b32_e32 v5, 1, v0
	v_and_b32_e32 v4, 31, v0
	v_lshl_add_u64 v[156:157], s[0:1], 0, v[2:3]
	v_and_b32_e32 v5, 16, v5
	s_movk_i32 s0, 0x110
	v_ashrrev_i32_e32 v11, 4, v0
	v_mad_u32_u24 v225, v4, s0, v5
	v_lshl_or_b32 v4, v11, 10, v10
	v_ashrrev_i32_e32 v5, 31, v4
	v_lshl_add_u64 v[158:159], v[4:5], 1, s[34:35]
	v_add_u32_e32 v5, 0x200, v0
	v_ashrrev_i32_e32 v5, 4, v5
	v_ashrrev_i32_e32 v223, 6, v0
	v_lshl_or_b32 v6, v5, 10, v10
	v_add_u32_e32 v0, 0x400, v0
	v_ashrrev_i32_e32 v7, 31, v6
	v_ashrrev_i32_e32 v0, 4, v0
	v_lshl_add_u64 v[160:161], v[6:7], 1, s[34:35]
	v_add_u32_e32 v7, s24, v0
	v_mul_lo_u32 v226, v11, s0
	v_mul_lo_u32 v227, v5, s0
	v_mul_lo_u32 v228, v0, s0
	v_readlane_b32 s0, v255, 23
	v_lshl_or_b32 v8, v7, 10, v10
	v_readlane_b32 s1, v255, 24
	v_ashrrev_i32_e32 v9, 31, v8
	v_add_lshl_u32 v0, v0, s55, 10
	v_lshl_add_u64 v[164:165], s[0:1], 0, v[2:3]
	s_movk_i32 s0, 0x80
	v_lshl_add_u64 v[162:163], v[8:9], 1, s[34:35]
	v_or_b32_e32 v229, 0x80, v4
	v_or3_b32 v230, v0, v10, s0
	v_or_b32_e32 v231, 0x80, v6
	v_mov_b32_e32 v232, v223
	s_waitcnt vmcnt(0)
	s_barrier
	v_readlane_b32 s10, v252, 10
	v_readlane_b32 s11, v252, 11
	v_readlane_b32 s0, v255, 42
	s_nop 3
	s_lshl_b32 s0, s0, 2
	s_add_u32 s0, s0, s73
	s_lshl_b32 s0, s0, 3
	s_add_u32 s10, s10, s0
	s_addc_u32 s11, s11, 0
	v_readfirstlane_b32 s0, v223
	s_nop 3
	s_cmp_lg_u32 s0, 0
	s_cbranch_scc1 .Lm3u_claim
	s_mov_b64 s[2:3], exec
	s_mov_b64 exec, 1
	s_getreg_b32 s0, hwreg(HW_REG_XCC_ID, 0, 4)
	s_add_u32 s0, s0, 1
	v_mov_b32_e32 v2, s0
	global_atomic_or v1, v2, s[10:11] offset:4
	s_mov_b64 exec, s[2:3]
	s_branch .Lm3u_claim
.LBB0_458:
	s_or_b64 exec, exec, s[56:57]
	v_readlane_b32 s10, v252, 10
	v_readlane_b32 s11, v252, 11
	v_readlane_b32 s0, v255, 42
	s_nop 3
	s_lshl_b32 s0, s0, 2
	s_add_u32 s0, s0, s73
	s_lshl_b32 s0, s0, 3
	s_add_u32 s10, s10, s0
	s_addc_u32 s11, s11, 0
.Lm3u_claim:
	v_readfirstlane_b32 s0, v223
	v_mov_b32_e32 v2, 0x20408
	s_nop 3
	s_cmp_lg_u32 s0, 0
	s_cbranch_scc1 .Lm3u_c_w
	s_mov_b64 s[2:3], exec
	s_mov_b64 exec, 1
	v_mov_b32_e32 v3, 1
	global_atomic_add v3, v1, v3, s[10:11] sc0
	s_waitcnt vmcnt(0)
	ds_write_b32 v2, v3
	s_waitcnt lgkmcnt(0)
	s_mov_b64 exec, s[2:3]
.Lm3u_c_w:
	s_barrier
	ds_read_b32 v3, v2
	s_waitcnt lgkmcnt(0)
	v_readfirstlane_b32 s31, v3
	s_nop 3
	s_cmp_ge_u32 s31, 11
	s_cbranch_scc1 .LBB0_312
	s_lshl_b32 s2, s31, 3
	v_add_u32_e32 v232, s2, v223

; DI int otid() { int t = threadIdx.x; asm volatile("" : "+v"(t)); return t; }
; DI const bf16_t* wp(const Params& p, int l, size_t off) { return (const bf16_t*)(p.ws + OFF_WP) + (size_t)l * PW_LAYER + off; }
;     ...
;     constexpr int KS = K / 16, NCH = K / A_CHUNK, PD = 4;
;     const int tid = otid(), wave = tid >> 6, lane = tid & 63, r = lane & 31, h = lane >> 5;
;     const u32x4* Bw = (const u32x4*)Wp;
; #pragma unroll 1
;     for (int pass = 0; pass * NWAVE < NU; ++pass) {
;         const int unit = pass * NWAVE + wave;
;         const bool active = unit < NU;
;         const int ucl = active ? unit : NU - 1;
;         const u32x4* bp = Bw + (size_t)(ucl * NT) * 64 + lane;
; template <int MT> DI void phaseB(const Params& p, int l, int t, unsigned char* lds) {
;     ...
;     EpiUp<MT> eu; eu.priv = priv; eu.d2 = d2;
;     eu.halo = (float*)(ws + OFF_UHALO) + (size_t)t * 2 * DFF2;
;     eu.pconv = t == NTILE - 1 ? p.out + O_PCONV + (size_t)l * 2 * DFF2 : nullptr;
;     eu.sconv = p.out + O_SCONV + ((size_t)l * 8 + 2 * t) * 2 * DFF2;
;     gemm64<1024, MT>(xb, DM, d2, wp(p, l, PW_UP), DFF2 / UW, lds, eu);
.LBB0_705:
	v_readlane_b32 s0, v254, 57
	s_cmp_lt_u32 s0, 4
	s_cbranch_scc1 .Lhu_done
	s_cmp_gt_u32 s0, 31
	s_cbranch_scc1 .Lhu_done
	v_writelane_b32 v246, s0, 0
	v_writelane_b32 v246, s1, 1
	v_writelane_b32 v246, s2, 2
	v_writelane_b32 v246, s3, 3
	v_writelane_b32 v246, s4, 4
	v_writelane_b32 v246, s5, 5
	v_writelane_b32 v246, s6, 6
	v_writelane_b32 v246, s7, 7
	v_writelane_b32 v246, s8, 8
	v_writelane_b32 v246, s9, 9
	v_writelane_b32 v246, s10, 10
	v_writelane_b32 v246, s11, 11
	v_writelane_b32 v246, s12, 12
	v_writelane_b32 v246, s13, 13
	v_writelane_b32 v246, s14, 14
	v_writelane_b32 v246, s15, 15
	v_writelane_b32 v246, s16, 16
	v_writelane_b32 v246, s17, 17
	v_writelane_b32 v246, s18, 18
	v_writelane_b32 v246, s19, 19
	v_writelane_b32 v246, s20, 20
	v_writelane_b32 v246, s21, 21
	v_writelane_b32 v246, s22, 22
	v_writelane_b32 v246, s23, 23
	v_writelane_b32 v246, s24, 24
	v_writelane_b32 v246, s25, 25
	v_writelane_b32 v246, s26, 26
	v_writelane_b32 v246, s27, 27
	v_writelane_b32 v246, s28, 28
	v_writelane_b32 v246, s29, 29
	v_writelane_b32 v246, s30, 30
	v_writelane_b32 v246, s31, 31
	v_writelane_b32 v246, s32, 32
	v_writelane_b32 v246, s33, 33
	v_writelane_b32 v246, s34, 34
	v_writelane_b32 v246, s35, 35
	v_writelane_b32 v246, s36, 36
	v_writelane_b32 v246, s37, 37
	v_writelane_b32 v246, s38, 38
	v_writelane_b32 v246, s39, 39
	v_writelane_b32 v246, s40, 40
	v_writelane_b32 v246, s41, 41
	v_writelane_b32 v246, s42, 42
	v_writelane_b32 v246, s43, 43
	v_writelane_b32 v246, s44, 44
	v_writelane_b32 v246, s45, 45
	v_writelane_b32 v246, s46, 46
	v_writelane_b32 v246, s47, 47
	v_writelane_b32 v246, s48, 48
	v_writelane_b32 v246, s49, 49
	v_writelane_b32 v246, s50, 50
	v_writelane_b32 v246, s51, 51
	v_writelane_b32 v246, s52, 52
	v_writelane_b32 v246, s53, 53
	v_writelane_b32 v246, s54, 54
	v_writelane_b32 v246, s55, 55
	v_writelane_b32 v246, s56, 56
	v_writelane_b32 v246, s57, 57
	v_writelane_b32 v246, s58, 58
	v_writelane_b32 v246, s59, 59
	v_writelane_b32 v246, s60, 60
	v_writelane_b32 v246, s61, 61
	v_writelane_b32 v246, s62, 62
	v_writelane_b32 v246, s63, 63
	v_writelane_b32 v247, s64, 0
	v_writelane_b32 v247, s65, 1
	v_writelane_b32 v247, s66, 2
	v_writelane_b32 v247, s67, 3
	v_writelane_b32 v247, s68, 4
	v_writelane_b32 v247, s69, 5
	v_writelane_b32 v247, s70, 6
	v_writelane_b32 v247, s71, 7
	v_writelane_b32 v247, s72, 8
	v_writelane_b32 v247, s73, 9
	v_writelane_b32 v247, s74, 10
	v_writelane_b32 v247, s75, 11
	v_writelane_b32 v247, s76, 12
	v_writelane_b32 v247, s77, 13
	v_writelane_b32 v247, s78, 14
	v_writelane_b32 v247, s79, 15
	v_writelane_b32 v247, s80, 16
	v_writelane_b32 v247, s81, 17
	v_writelane_b32 v247, s82, 18
	v_writelane_b32 v247, s83, 19
	v_writelane_b32 v247, s84, 20
	v_writelane_b32 v247, s85, 21
	v_writelane_b32 v247, s86, 22
	v_writelane_b32 v247, s87, 23
	v_writelane_b32 v247, s88, 24
	v_writelane_b32 v247, s89, 25
	v_writelane_b32 v247, s90, 26
	v_writelane_b32 v247, s91, 27
	v_writelane_b32 v247, s92, 28
	v_writelane_b32 v247, s93, 29
	v_writelane_b32 v247, s94, 30
	v_writelane_b32 v247, s95, 31
	v_writelane_b32 v247, s96, 32
	v_writelane_b32 v247, s97, 33
	v_writelane_b32 v247, s98, 34
	v_writelane_b32 v247, s99, 35
	v_writelane_b32 v247, s100, 36
	v_writelane_b32 v247, s101, 37
	v_writelane_b32 v247, vcc_lo, 38
	v_writelane_b32 v247, vcc_hi, 39
	s_getreg_b32 s70, hwreg(HW_REG_XCC_ID, 0, 4)
	s_mov_b32 s43, 0xb0000
	s_movk_i32 s44, 0x1600
	s_mov_b32 s65, 0
	v_readlane_b32 s66, v252, 10
	v_readlane_b32 s67, v252, 11
	v_readlane_b32 s68, v254, 57
	s_mov_b32 s69, 0
	v_lshrrev_b32_e32 v223, 6, v176
.Lhu_target:
	s_add_u32 s71, s68, s69
	s_and_b32 s71, s71, 3
	s_lshl_b32 s72, s60, 2
	s_add_u32 s72, s72, s71
	s_lshl_b32 s72, s72, 3
	s_add_u32 s74, s66, s72
	s_addc_u32 s75, s67, 0
	v_readfirstlane_b32 s76, v223
	v_mov_b32_e32 v3, 0x2040c
	s_nop 3
	s_cmp_lg_u32 s76, 0
	s_cbranch_scc1 .Lhu_polled
	s_mov_b64 s[78:79], exec
	s_mov_b64 exec, 1
	s_mov_b32 s77, 0
.Lhu_poll:
	v_mov_b32_e32 v2, 0
	global_atomic_add v2, v1, v2, s[74:75] offset:4 sc0
	s_waitcnt vmcnt(0)
	v_readfirstlane_b32 s0, v2
	s_nop 3
	s_cmp_lg_u32 s0, 0
	s_cbranch_scc1 .Lhu_got
	s_sleep 40
	s_add_u32 s77, s77, 1
	s_cmp_lt_u32 s77, 500
	s_cbranch_scc1 .Lhu_poll
.Lhu_got:
	ds_write_b32 v3, v2
	s_waitcnt lgkmcnt(0)
	s_mov_b64 exec, s[78:79]
.Lhu_polled:
	s_barrier
	ds_read_b32 v2, v3
	s_waitcnt lgkmcnt(0)
	v_readfirstlane_b32 s0, v2
	s_nop 3
	s_cmp_eq_u32 s0, 0
	s_cbranch_scc1 .Lhu_next
	s_sub_u32 s0, s0, 1
	s_cmp_lg_u32 s0, s70
	s_cbranch_scc1 .Lhu_next
	buffer_inv sc1
	s_waitcnt vmcnt(0)
	v_readlane_b32 s0, v252, 4
	v_readlane_b32 s1, v252, 5
	s_lshl_b32 s2, s71, 17
	s_add_u32 s34, s0, 0x7c00000
	s_addc_u32 s35, s1, 0
	s_add_u32 s34, s34, s2
	s_addc_u32 s35, s35, 0
	s_mul_i32 s2, s71, 0xb0000
	s_add_u32 s6, s0, 0x9c40000
	s_addc_u32 s7, s1, 0
	s_add_u32 s6, s6, s2
	s_addc_u32 s7, s7, 0
	s_mul_i32 s2, s71, 0xb000
	s_add_u32 s8, s0, 0x175f0000
	s_addc_u32 s9, s1, 0
	s_add_u32 s8, s8, s2
	s_addc_u32 s9, s9, 0
	v_readlane_b32 s10, v252, 2
	v_readlane_b32 s11, v252, 3
	s_mul_i32 s2, s60, 0x58000
	s_mul_i32 s3, s71, 0x16000
	s_add_u32 s2, s2, s3
	s_add_u32 s2, s2, 0x4fac000
	s_add_u32 s28, s10, s2
	s_addc_u32 s29, s11, 0
	s_mul_i32 s2, s60, 0x1f00000
	s_add_u32 s14, s0, s2
	s_addc_u32 s15, s1, 0
	s_add_u32 s12, s14, 0xe80000
	s_addc_u32 s13, s15, 0
	s_lshl_b32 s2, s71, 5
	s_sub_u32 s24, 0x3fc0, s2
	s_mov_b32 s55, s24
	s_sub_u32 s59, 0x4000, s2
	v_mov_b32_e32 v0, v176
	v_lshlrev_b32_e32 v5, 3, v0
	v_and_b32_e32 v2, 63, v0
	s_mov_b32 s0, s12
	v_and_b32_e32 v10, 0x78, v5
	v_lshlrev_b32_e32 v5, 4, v0
	v_lshlrev_b32_e32 v2, 4, v2
	v_mov_b32_e32 v3, v1
	s_mov_b32 s1, s13
	v_and_b32_e32 v224, 0xf0, v5
	v_lshrrev_b32_e32 v5, 1, v0
	v_and_b32_e32 v4, 31, v0
	v_lshl_add_u64 v[156:157], s[0:1], 0, v[2:3]
	v_and_b32_e32 v5, 16, v5
	s_movk_i32 s0, 0x110
	v_ashrrev_i32_e32 v11, 4, v0
	v_mad_u32_u24 v225, v4, s0, v5
	v_lshl_or_b32 v4, v11, 10, v10
	v_ashrrev_i32_e32 v5, 31, v4
	v_lshl_add_u64 v[158:159], v[4:5], 1, s[34:35]
	v_add_u32_e32 v5, 0x200, v0
	v_ashrrev_i32_e32 v5, 4, v5
	v_ashrrev_i32_e32 v223, 6, v0
	v_lshl_or_b32 v6, v5, 10, v10
	v_add_u32_e32 v0, 0x400, v0
	v_ashrrev_i32_e32 v7, 31, v6
	v_ashrrev_i32_e32 v0, 4, v0
	v_lshl_add_u64 v[160:161], v[6:7], 1, s[34:35]
	v_add_u32_e32 v7, s24, v0
	v_mul_lo_u32 v226, v11, s0
	v_mul_lo_u32 v227, v5, s0
	v_mul_lo_u32 v228, v0, s0
	s_mov_b32 s0, s14
	v_lshl_or_b32 v8, v7, 10, v10
	s_mov_b32 s1, s15
	v_ashrrev_i32_e32 v9, 31, v8
	v_add_lshl_u32 v0, v0, s55, 10
	v_lshl_add_u64 v[164:165], s[0:1], 0, v[2:3]
	s_movk_i32 s0, 0x80
	v_lshl_add_u64 v[162:163], v[8:9], 1, s[34:35]
	v_or_b32_e32 v229, 0x80, v4
	v_or3_b32 v230, v0, v10, s0
	v_or_b32_e32 v231, 0x80, v6
	v_mov_b32_e32 v232, v223
.Lhu_claim:
	v_readfirstlane_b32 s0, v223
	v_mov_b32_e32 v2, 0x20408
	s_nop 3
	s_cmp_lg_u32 s0, 0
	s_cbranch_scc1 .Lhu_c_w
	s_mov_b64 s[2:3], exec
	s_mov_b64 exec, 1
	v_mov_b32_e32 v3, 1
	global_atomic_add v3, v1, v3, s[74:75] sc0
	s_waitcnt vmcnt(0)
	ds_write_b32 v2, v3
	s_waitcnt lgkmcnt(0)
	s_mov_b64 exec, s[2:3]

;     ...
; #pragma unroll 1
;     for (int pass = 0; pass * NWAVE < NU; ++pass) {
;         const int unit = pass * NWAVE + wave;
.Lhu_latch:
	s_or_b64 exec, exec, s[56:57]
	s_branch .Lhu_claim
.Lhu_next:
	s_add_u32 s69, s69, 1
	s_cmp_lt_u32 s69, 4
	s_cbranch_scc1 .Lhu_target
	v_readlane_b32 s0, v246, 0
	v_readlane_b32 s1, v246, 1
	v_readlane_b32 s2, v246, 2
	v_readlane_b32 s3, v246, 3
	v_readlane_b32 s4, v246, 4
	v_readlane_b32 s5, v246, 5
	v_readlane_b32 s6, v246, 6
	v_readlane_b32 s7, v246, 7
	v_readlane_b32 s8, v246, 8
	v_readlane_b32 s9, v246, 9
	v_readlane_b32 s10, v246, 10
	v_readlane_b32 s11, v246, 11
	v_readlane_b32 s12, v246, 12
	v_readlane_b32 s13, v246, 13
	v_readlane_b32 s14, v246, 14
	v_readlane_b32 s15, v246, 15
	v_readlane_b32 s16, v246, 16
	v_readlane_b32 s17, v246, 17
	v_readlane_b32 s18, v246, 18
	v_readlane_b32 s19, v246, 19
	v_readlane_b32 s20, v246, 20
	v_readlane_b32 s21, v246, 21
	v_readlane_b32 s22, v246, 22
	v_readlane_b32 s23, v246, 23
	v_readlane_b32 s24, v246, 24
	v_readlane_b32 s25, v246, 25
	v_readlane_b32 s26, v246, 26
	v_readlane_b32 s27, v246, 27
	v_readlane_b32 s28, v246, 28
	v_readlane_b32 s29, v246, 29
	v_readlane_b32 s30, v246, 30
	v_readlane_b32 s31, v246, 31
	v_readlane_b32 s32, v246, 32
	v_readlane_b32 s33, v246, 33
	v_readlane_b32 s34, v246, 34
	v_readlane_b32 s35, v246, 35
	v_readlane_b32 s36, v246, 36
	v_readlane_b32 s37, v246, 37
	v_readlane_b32 s38, v246, 38
	v_readlane_b32 s39, v246, 39
	v_readlane_b32 s40, v246, 40
	v_readlane_b32 s41, v246, 41
	v_readlane_b32 s42, v246, 42
	v_readlane_b32 s43, v246, 43
	v_readlane_b32 s44, v246, 44
	v_readlane_b32 s45, v246, 45
	v_readlane_b32 s46, v246, 46
	v_readlane_b32 s47, v246, 47
	v_readlane_b32 s48, v246, 48
	v_readlane_b32 s49, v246, 49
	v_readlane_b32 s50, v246, 50
	v_readlane_b32 s51, v246, 51
	v_readlane_b32 s52, v246, 52
	v_readlane_b32 s53, v246, 53
	v_readlane_b32 s54, v246, 54
	v_readlane_b32 s55, v246, 55
	v_readlane_b32 s56, v246, 56
	v_readlane_b32 s57, v246, 57
	v_readlane_b32 s58, v246, 58
	v_readlane_b32 s59, v246, 59
	v_readlane_b32 s60, v246, 60
	v_readlane_b32 s61, v246, 61
	v_readlane_b32 s62, v246, 62
	v_readlane_b32 s63, v246, 63
	v_readlane_b32 s64, v247, 0
	v_readlane_b32 s65, v247, 1
	v_readlane_b32 s66, v247, 2
	v_readlane_b32 s67, v247, 3
	v_readlane_b32 s68, v247, 4
	v_readlane_b32 s69, v247, 5
	v_readlane_b32 s70, v247, 6
	v_readlane_b32 s71, v247, 7
	v_readlane_b32 s72, v247, 8
	v_readlane_b32 s73, v247, 9
	v_readlane_b32 s74, v247, 10
	v_readlane_b32 s75, v247, 11
	v_readlane_b32 s76, v247, 12
	v_readlane_b32 s77, v247, 13
	v_readlane_b32 s78, v247, 14
	v_readlane_b32 s79, v247, 15
	v_readlane_b32 s80, v247, 16
	v_readlane_b32 s81, v247, 17
	v_readlane_b32 s82, v247, 18
	v_readlane_b32 s83, v247, 19
	v_readlane_b32 s84, v247, 20
	v_readlane_b32 s85, v247, 21
	v_readlane_b32 s86, v247, 22
	v_readlane_b32 s87, v247, 23
	v_readlane_b32 s88, v247, 24
	v_readlane_b32 s89, v247, 25
	v_readlane_b32 s90, v247, 26
	v_readlane_b32 s91, v247, 27
	v_readlane_b32 s92, v247, 28
	v_readlane_b32 s93, v247, 29
	v_readlane_b32 s94, v247, 30
	v_readlane_b32 s95, v247, 31
	v_readlane_b32 s96, v247, 32
	v_readlane_b32 s97, v247, 33
	v_readlane_b32 s98, v247, 34
	v_readlane_b32 s99, v247, 35
	v_readlane_b32 s100, v247, 36
	v_readlane_b32 s101, v247, 37
	v_readlane_b32 vcc_lo, v247, 38
	v_readlane_b32 vcc_hi, v247, 39
